# on top of the attention trims: first softmax MFMA wait filled with two conversions, gMLP second-tile u loads issued early, L1 invalidate of the first barrier in the arrival-atomic shadow
# speedup vs baseline: 1.0051x; 1.0036x over previous
; __device__ __forceinline__ unsigned pk2(float lo, float hi) { f32x2 v = {lo, hi}; bf16x2_t b = __builtin_convertvector(v, bf16x2_t); return __builtin_bit_cast(unsigned, b); }
; __device__ __forceinline__ void tile_compute(const bf16x8 (&kf)[4], const bf16x8 (&vf)[2][2], const bf16x8 (&qf)[4], unsigned long long w0, unsigned long long w1,
;                                              float shift, f32x16& o0, f32x16& o1, f32x16& zacc, const bf16x8& ones) {
;     ...
;     unsigned pw[8];
; #pragma unroll
;     for (int eg = 0; eg < 2; ++eg) {
;         const unsigned long long w = eg ? w1 : w0;
;         const unsigned wl = (unsigned)w, wh = (unsigned)(w >> 32);
;         float pv[8];
; #pragma unroll
;         for (int p = 0; p < 4; ++p) {
;             pv[p] = (float)((wl >> (8 * p)) & 0xffu) * __builtin_amdgcn_exp2f(st[8 * eg + p]);
;             pv[4 + p] = (float)((wh >> (8 * p)) & 0xffu) * __builtin_amdgcn_exp2f(st[8 * eg + 4 + p]);
;         }
; #pragma unroll
;         for (int p = 0; p < 4; ++p) pw[4 * eg + p] = pk2(pv[2 * p], pv[2 * p + 1]);
;     }
;     const bf16x8 pf0 = __builtin_bit_cast(bf16x8, (u32x4){pw[0], pw[1], pw[2], pw[3]});
;     const bf16x8 pf1 = __builtin_bit_cast(bf16x8, (u32x4){pw[4], pw[5], pw[6], pw[7]});
;     o0 = __builtin_amdgcn_mfma_f32_32x32x16_bf16(vf[0][0], pf0, o0, 0, 0, 0);
;     o1 = __builtin_amdgcn_mfma_f32_32x32x16_bf16(vf[1][0], pf0, o1, 0, 0, 0);
;     zacc = __builtin_amdgcn_mfma_f32_32x32x16_bf16(ones, pf0, zacc, 0, 0, 0);
;     o0 = __builtin_amdgcn_mfma_f32_32x32x16_bf16(vf[0][1], pf1, o0, 0, 0, 0);
;     o1 = __builtin_amdgcn_mfma_f32_32x32x16_bf16(vf[1][1], pf1, o1, 0, 0, 0);
;     zacc = __builtin_amdgcn_mfma_f32_32x32x16_bf16(ones, pf1, zacc, 0, 0, 0);
.LBB0_170:
	v_cvt_f32_ubyte1_e32 v175, v212
	v_cvt_f32_ubyte0_e32 v174, v212
	s_nop 3
	v_exp_f32_e32 v66, v66
	s_nop 3
	v_exp_f32_e32 v67, v67
	v_exp_f32_e32 v70, v70
	v_exp_f32_e32 v71, v71
	v_exp_f32_e32 v68, v68
	v_exp_f32_e32 v69, v69
	v_exp_f32_e32 v72, v72
	v_exp_f32_e32 v73, v73
	v_pk_mul_f32 v[66:67], v[66:67], v[174:175]
	v_cvt_f32_ubyte1_e32 v175, v213
	v_cvt_f32_ubyte0_e32 v174, v213
	v_pk_mul_f32 v[70:71], v[70:71], v[174:175]
	v_cvt_f32_ubyte3_e32 v175, v212
	v_cvt_f32_ubyte2_e32 v174, v212
	v_pk_mul_f32 v[68:69], v[68:69], v[174:175]
	v_cvt_f32_ubyte3_e32 v175, v213
	v_cvt_f32_ubyte2_e32 v174, v213
	v_pk_mul_f32 v[72:73], v[72:73], v[174:175]
	v_cvt_pk_bf16_f32 v66, v66, v67
	v_cvt_pk_bf16_f32 v67, v68, v69
	v_cvt_pk_bf16_f32 v68, v70, v71
	v_exp_f32_e32 v70, v74
	v_exp_f32_e32 v71, v75
	v_cvt_pk_bf16_f32 v69, v72, v73
	v_exp_f32_e32 v72, v78
	v_exp_f32_e32 v73, v79
	s_waitcnt vmcnt(4)
	v_mfma_f32_32x32x16_bf16 v[18:33], v[162:165], v[66:69], v[18:33]
	v_cvt_f32_ubyte1_e32 v75, v210
	v_cvt_f32_ubyte0_e32 v74, v210
	v_mul_f32_e64 v70, v70, v74
	v_mul_f32_e64 v71, v71, v75
	v_cvt_f32_ubyte1_e32 v75, v211
	v_cvt_f32_ubyte0_e32 v74, v211
	v_pk_mul_f32 v[72:73], v[72:73], v[74:75]
	v_exp_f32_e32 v74, v76
	v_mfma_f32_32x32x16_bf16 v[34:49], v[158:161], v[66:69], v[34:49]
	v_exp_f32_e32 v75, v77
	v_exp_f32_e32 v76, v80
	v_exp_f32_e32 v77, v81
	v_cvt_f32_ubyte3_e32 v79, v210
	v_cvt_f32_ubyte2_e32 v78, v210
	v_pk_mul_f32 v[74:75], v[74:75], v[78:79]
	s_cmp_lt_i32 s24, 26
	v_mfma_f32_32x32x16_bf16 v[50:65], v[154:157], v[66:69], v[50:65]
	v_cvt_f32_ubyte3_e32 v67, v211
	v_cvt_f32_ubyte2_e32 v66, v211
	v_mul_f32_e64 v76, v76, v66
	v_mul_f32_e64 v77, v77, v67
	v_cvt_pk_bf16_f32 v66, v70, v71
	v_cvt_pk_bf16_f32 v67, v74, v75
	v_cvt_pk_bf16_f32 v68, v72, v73
	v_cvt_pk_bf16_f32 v69, v76, v77
	s_cselect_b64 s[4:5], -1, 0
	s_cmp_lt_i32 s23, 10
	v_mfma_f32_32x32x16_bf16 v[18:33], v[166:169], v[66:69], v[18:33]
	s_cselect_b64 s[0:1], -1, 0
	s_or_b64 s[4:5], s[4:5], s[0:1]
	s_and_b64 vcc, exec, s[4:5]
	v_mfma_f32_32x32x16_bf16 v[34:49], v[170:173], v[66:69], v[34:49]
	v_mfma_f32_32x32x16_bf16 v[50:65], v[154:157], v[66:69], v[50:65]
	s_cbranch_vccz .LBB0_247

; __device__ __forceinline__ unsigned pk2(float lo, float hi) { f32x2 v = {lo, hi}; bf16x2_t b = __builtin_convertvector(v, bf16x2_t); return __builtin_bit_cast(unsigned, b); }
; __device__ __forceinline__ void tile_compute(const bf16x8 (&kf)[4], const bf16x8 (&vf)[2][2], const bf16x8 (&qf)[4], unsigned long long w0, unsigned long long w1,
;                                              float shift, f32x16& o0, f32x16& o1, f32x16& zacc, const bf16x8& ones) {
;     ...
;     unsigned pw[8];
; #pragma unroll
;     for (int eg = 0; eg < 2; ++eg) {
;         const unsigned long long w = eg ? w1 : w0;
;         const unsigned wl = (unsigned)w, wh = (unsigned)(w >> 32);
;         float pv[8];
; #pragma unroll
;         for (int p = 0; p < 4; ++p) {
;             pv[p] = (float)((wl >> (8 * p)) & 0xffu) * __builtin_amdgcn_exp2f(st[8 * eg + p]);
;             pv[4 + p] = (float)((wh >> (8 * p)) & 0xffu) * __builtin_amdgcn_exp2f(st[8 * eg + 4 + p]);
;         }
; #pragma unroll
;         for (int p = 0; p < 4; ++p) pw[4 * eg + p] = pk2(pv[2 * p], pv[2 * p + 1]);
;     }
;     const bf16x8 pf0 = __builtin_bit_cast(bf16x8, (u32x4){pw[0], pw[1], pw[2], pw[3]});
;     const bf16x8 pf1 = __builtin_bit_cast(bf16x8, (u32x4){pw[4], pw[5], pw[6], pw[7]});
;     o0 = __builtin_amdgcn_mfma_f32_32x32x16_bf16(vf[0][0], pf0, o0, 0, 0, 0);
;     o1 = __builtin_amdgcn_mfma_f32_32x32x16_bf16(vf[1][0], pf0, o1, 0, 0, 0);
;     zacc = __builtin_amdgcn_mfma_f32_32x32x16_bf16(ones, pf0, zacc, 0, 0, 0);
;     o0 = __builtin_amdgcn_mfma_f32_32x32x16_bf16(vf[0][1], pf1, o0, 0, 0, 0);
;     o1 = __builtin_amdgcn_mfma_f32_32x32x16_bf16(vf[1][1], pf1, o1, 0, 0, 0);
;     zacc = __builtin_amdgcn_mfma_f32_32x32x16_bf16(ones, pf1, zacc, 0, 0, 0);
.LBB0_250:
	v_cvt_f32_ubyte1_e32 v175, v212
	v_cvt_f32_ubyte0_e32 v174, v212
	s_nop 3
	v_exp_f32_e32 v66, v66
	s_nop 3
	v_exp_f32_e32 v67, v67
	v_exp_f32_e32 v70, v70
	v_exp_f32_e32 v71, v71
	v_exp_f32_e32 v68, v68
	v_exp_f32_e32 v69, v69
	v_exp_f32_e32 v72, v72
	v_exp_f32_e32 v73, v73
	v_pk_mul_f32 v[66:67], v[66:67], v[174:175]
	v_cvt_f32_ubyte1_e32 v175, v213
	v_cvt_f32_ubyte0_e32 v174, v213
	v_pk_mul_f32 v[70:71], v[70:71], v[174:175]
	v_cvt_f32_ubyte3_e32 v175, v212
	v_cvt_f32_ubyte2_e32 v174, v212
	v_pk_mul_f32 v[68:69], v[68:69], v[174:175]
	v_cvt_f32_ubyte3_e32 v175, v213
	v_cvt_f32_ubyte2_e32 v174, v213
	v_pk_mul_f32 v[72:73], v[72:73], v[174:175]
	v_cvt_pk_bf16_f32 v66, v66, v67
	v_cvt_pk_bf16_f32 v67, v68, v69
	v_cvt_pk_bf16_f32 v68, v70, v71
	v_exp_f32_e32 v70, v74
	v_exp_f32_e32 v71, v75
	v_cvt_pk_bf16_f32 v69, v72, v73
	v_exp_f32_e32 v72, v78
	v_exp_f32_e32 v73, v79
	s_waitcnt vmcnt(4)
	v_mfma_f32_32x32x16_bf16 v[18:33], v[162:165], v[66:69], v[18:33]
	v_cvt_f32_ubyte1_e32 v75, v210
	v_cvt_f32_ubyte0_e32 v74, v210
	v_mul_f32_e64 v70, v70, v74
	v_mul_f32_e64 v71, v71, v75
	v_cvt_f32_ubyte1_e32 v75, v211
	v_cvt_f32_ubyte0_e32 v74, v211
	v_pk_mul_f32 v[72:73], v[72:73], v[74:75]
	v_exp_f32_e32 v74, v76
	v_mfma_f32_32x32x16_bf16 v[34:49], v[158:161], v[66:69], v[34:49]
	v_exp_f32_e32 v75, v77
	v_exp_f32_e32 v76, v80
	v_exp_f32_e32 v77, v81
	v_cvt_f32_ubyte3_e32 v79, v210
	v_cvt_f32_ubyte2_e32 v78, v210
	v_pk_mul_f32 v[74:75], v[74:75], v[78:79]
	s_cmp_lt_i32 s19, 26
	v_mfma_f32_32x32x16_bf16 v[50:65], v[154:157], v[66:69], v[50:65]
	v_cvt_f32_ubyte3_e32 v67, v211
	v_cvt_f32_ubyte2_e32 v66, v211
	v_mul_f32_e64 v76, v76, v66
	v_mul_f32_e64 v77, v77, v67
	v_cvt_pk_bf16_f32 v66, v70, v71
	v_cvt_pk_bf16_f32 v67, v74, v75
	v_cvt_pk_bf16_f32 v68, v72, v73
	v_cvt_pk_bf16_f32 v69, v76, v77
	s_cselect_b64 s[4:5], -1, 0
	s_cmp_lt_i32 s14, 10
	v_mfma_f32_32x32x16_bf16 v[18:33], v[166:169], v[66:69], v[18:33]
	s_cselect_b64 s[0:1], -1, 0
	s_or_b64 s[4:5], s[4:5], s[0:1]
	s_and_b64 vcc, exec, s[4:5]
	v_mfma_f32_32x32x16_bf16 v[34:49], v[170:173], v[66:69], v[34:49]
	v_mfma_f32_32x32x16_bf16 v[50:65], v[154:157], v[66:69], v[50:65]
	s_cbranch_vccz .LBB0_327

; __device__ __forceinline__ unsigned pk2(float lo, float hi) { f32x2 v = {lo, hi}; bf16x2_t b = __builtin_convertvector(v, bf16x2_t); return __builtin_bit_cast(unsigned, b); }
; __device__ __forceinline__ void tile_compute(const bf16x8 (&kf)[4], const bf16x8 (&vf)[2][2], const bf16x8 (&qf)[4], unsigned long long w0, unsigned long long w1,
;                                              float shift, f32x16& o0, f32x16& o1, f32x16& zacc, const bf16x8& ones) {
;     ...
;     unsigned pw[8];
; #pragma unroll
;     for (int eg = 0; eg < 2; ++eg) {
;         const unsigned long long w = eg ? w1 : w0;
;         const unsigned wl = (unsigned)w, wh = (unsigned)(w >> 32);
;         float pv[8];
; #pragma unroll
;         for (int p = 0; p < 4; ++p) {
;             pv[p] = (float)((wl >> (8 * p)) & 0xffu) * __builtin_amdgcn_exp2f(st[8 * eg + p]);
;             pv[4 + p] = (float)((wh >> (8 * p)) & 0xffu) * __builtin_amdgcn_exp2f(st[8 * eg + 4 + p]);
;         }
; #pragma unroll
;         for (int p = 0; p < 4; ++p) pw[4 * eg + p] = pk2(pv[2 * p], pv[2 * p + 1]);
;     }
;     const bf16x8 pf0 = __builtin_bit_cast(bf16x8, (u32x4){pw[0], pw[1], pw[2], pw[3]});
;     const bf16x8 pf1 = __builtin_bit_cast(bf16x8, (u32x4){pw[4], pw[5], pw[6], pw[7]});
;     o0 = __builtin_amdgcn_mfma_f32_32x32x16_bf16(vf[0][0], pf0, o0, 0, 0, 0);
;     o1 = __builtin_amdgcn_mfma_f32_32x32x16_bf16(vf[1][0], pf0, o1, 0, 0, 0);
;     zacc = __builtin_amdgcn_mfma_f32_32x32x16_bf16(ones, pf0, zacc, 0, 0, 0);
;     o0 = __builtin_amdgcn_mfma_f32_32x32x16_bf16(vf[0][1], pf1, o0, 0, 0, 0);
;     o1 = __builtin_amdgcn_mfma_f32_32x32x16_bf16(vf[1][1], pf1, o1, 0, 0, 0);
;     zacc = __builtin_amdgcn_mfma_f32_32x32x16_bf16(ones, pf1, zacc, 0, 0, 0);
.LBB0_334:
	v_cvt_f32_ubyte1_e32 v175, v212
	v_cvt_f32_ubyte0_e32 v174, v212
	s_nop 3
	v_exp_f32_e32 v66, v66
	s_nop 3
	v_exp_f32_e32 v67, v67
	v_exp_f32_e32 v70, v70
	v_exp_f32_e32 v71, v71
	v_exp_f32_e32 v68, v68
	v_exp_f32_e32 v69, v69
	v_exp_f32_e32 v72, v72
	v_exp_f32_e32 v73, v73
	v_pk_mul_f32 v[66:67], v[66:67], v[174:175]
	v_cvt_f32_ubyte1_e32 v175, v213
	v_cvt_f32_ubyte0_e32 v174, v213
	v_pk_mul_f32 v[70:71], v[70:71], v[174:175]
	v_cvt_f32_ubyte3_e32 v175, v212
	v_cvt_f32_ubyte2_e32 v174, v212
	v_pk_mul_f32 v[68:69], v[68:69], v[174:175]
	v_cvt_f32_ubyte3_e32 v175, v213
	v_cvt_f32_ubyte2_e32 v174, v213
	v_pk_mul_f32 v[72:73], v[72:73], v[174:175]
	v_cvt_pk_bf16_f32 v66, v66, v67
	v_cvt_pk_bf16_f32 v67, v68, v69
	v_cvt_pk_bf16_f32 v68, v70, v71
	v_exp_f32_e32 v70, v74
	v_exp_f32_e32 v71, v75
	v_cvt_pk_bf16_f32 v69, v72, v73
	v_exp_f32_e32 v72, v78
	v_exp_f32_e32 v73, v79
	v_mfma_f32_32x32x16_bf16 v[18:33], v[162:165], v[66:69], v[18:33]
	v_cvt_f32_ubyte1_e32 v75, v210
	v_cvt_f32_ubyte0_e32 v74, v210
	v_mul_f32_e64 v70, v70, v74
	v_mul_f32_e64 v71, v71, v75
	v_cvt_f32_ubyte1_e32 v75, v211
	v_cvt_f32_ubyte0_e32 v74, v211
	v_pk_mul_f32 v[72:73], v[72:73], v[74:75]
	v_exp_f32_e32 v74, v76
	v_mfma_f32_32x32x16_bf16 v[34:49], v[158:161], v[66:69], v[34:49]
	v_exp_f32_e32 v75, v77
	v_exp_f32_e32 v76, v80
	v_exp_f32_e32 v77, v81
	v_cvt_f32_ubyte3_e32 v79, v210
	v_cvt_f32_ubyte2_e32 v78, v210
	v_pk_mul_f32 v[74:75], v[74:75], v[78:79]
	s_cmp_lt_i32 s66, 26
	v_mfma_f32_32x32x16_bf16 v[50:65], v[154:157], v[66:69], v[50:65]
	v_cvt_f32_ubyte3_e32 v67, v211
	v_cvt_f32_ubyte2_e32 v66, v211
	v_mul_f32_e64 v76, v76, v66
	v_mul_f32_e64 v77, v77, v67
	v_cvt_pk_bf16_f32 v66, v70, v71
	v_cvt_pk_bf16_f32 v67, v74, v75
	v_cvt_pk_bf16_f32 v68, v72, v73
	v_cvt_pk_bf16_f32 v69, v76, v77
	s_cselect_b64 s[4:5], -1, 0
	s_cmp_lt_i32 s72, 10
	v_mfma_f32_32x32x16_bf16 v[18:33], v[166:169], v[66:69], v[18:33]
	s_cselect_b64 s[0:1], -1, 0
	s_or_b64 s[4:5], s[4:5], s[0:1]
	s_and_b64 vcc, exec, s[4:5]
	v_mfma_f32_32x32x16_bf16 v[34:49], v[170:173], v[66:69], v[34:49]
	v_mfma_f32_32x32x16_bf16 v[50:65], v[154:157], v[66:69], v[50:65]
	s_cbranch_vccz .LBB0_430

; __device__ __forceinline__ unsigned pk2(float lo, float hi) { f32x2 v = {lo, hi}; bf16x2_t b = __builtin_convertvector(v, bf16x2_t); return __builtin_bit_cast(unsigned, b); }
; __device__ __forceinline__ void tile_compute(const bf16x8 (&kf)[4], const bf16x8 (&vf)[2][2], const bf16x8 (&qf)[4], unsigned long long w0, unsigned long long w1,
;                                              float shift, f32x16& o0, f32x16& o1, f32x16& zacc, const bf16x8& ones) {
;     ...
;     unsigned pw[8];
; #pragma unroll
;     for (int eg = 0; eg < 2; ++eg) {
;         const unsigned long long w = eg ? w1 : w0;
;         const unsigned wl = (unsigned)w, wh = (unsigned)(w >> 32);
;         float pv[8];
; #pragma unroll
;         for (int p = 0; p < 4; ++p) {
;             pv[p] = (float)((wl >> (8 * p)) & 0xffu) * __builtin_amdgcn_exp2f(st[8 * eg + p]);
;             pv[4 + p] = (float)((wh >> (8 * p)) & 0xffu) * __builtin_amdgcn_exp2f(st[8 * eg + 4 + p]);
;         }
; #pragma unroll
;         for (int p = 0; p < 4; ++p) pw[4 * eg + p] = pk2(pv[2 * p], pv[2 * p + 1]);
;     }
;     const bf16x8 pf0 = __builtin_bit_cast(bf16x8, (u32x4){pw[0], pw[1], pw[2], pw[3]});
;     const bf16x8 pf1 = __builtin_bit_cast(bf16x8, (u32x4){pw[4], pw[5], pw[6], pw[7]});
;     o0 = __builtin_amdgcn_mfma_f32_32x32x16_bf16(vf[0][0], pf0, o0, 0, 0, 0);
;     o1 = __builtin_amdgcn_mfma_f32_32x32x16_bf16(vf[1][0], pf0, o1, 0, 0, 0);
;     zacc = __builtin_amdgcn_mfma_f32_32x32x16_bf16(ones, pf0, zacc, 0, 0, 0);
;     o0 = __builtin_amdgcn_mfma_f32_32x32x16_bf16(vf[0][1], pf1, o0, 0, 0, 0);
;     o1 = __builtin_amdgcn_mfma_f32_32x32x16_bf16(vf[1][1], pf1, o1, 0, 0, 0);
;     zacc = __builtin_amdgcn_mfma_f32_32x32x16_bf16(ones, pf1, zacc, 0, 0, 0);
.LBB0_437:
	v_cvt_f32_ubyte1_e32 v175, v212
	v_cvt_f32_ubyte0_e32 v174, v212
	s_nop 3
	v_exp_f32_e32 v66, v66
	s_nop 3
	v_exp_f32_e32 v67, v67
	v_exp_f32_e32 v70, v70
	v_exp_f32_e32 v71, v71
	v_exp_f32_e32 v68, v68
	v_exp_f32_e32 v69, v69
	v_exp_f32_e32 v72, v72
	v_exp_f32_e32 v73, v73
	v_pk_mul_f32 v[66:67], v[66:67], v[174:175]
	v_cvt_f32_ubyte1_e32 v175, v213
	v_cvt_f32_ubyte0_e32 v174, v213
	v_pk_mul_f32 v[70:71], v[70:71], v[174:175]
	v_cvt_f32_ubyte3_e32 v175, v212
	v_cvt_f32_ubyte2_e32 v174, v212
	v_pk_mul_f32 v[68:69], v[68:69], v[174:175]
	v_cvt_f32_ubyte3_e32 v175, v213
	v_cvt_f32_ubyte2_e32 v174, v213
	v_pk_mul_f32 v[72:73], v[72:73], v[174:175]
	v_cvt_pk_bf16_f32 v66, v66, v67
	v_cvt_pk_bf16_f32 v67, v68, v69
	v_cvt_pk_bf16_f32 v68, v70, v71
	v_exp_f32_e32 v70, v74
	v_exp_f32_e32 v71, v75
	v_cvt_pk_bf16_f32 v69, v72, v73
	v_exp_f32_e32 v72, v78
	v_exp_f32_e32 v73, v79
	v_mfma_f32_32x32x16_bf16 v[18:33], v[162:165], v[66:69], v[18:33]
	v_cvt_f32_ubyte1_e32 v75, v210
	v_cvt_f32_ubyte0_e32 v74, v210
	v_mul_f32_e64 v70, v70, v74
	v_mul_f32_e64 v71, v71, v75
	v_cvt_f32_ubyte1_e32 v75, v211
	v_cvt_f32_ubyte0_e32 v74, v211
	v_pk_mul_f32 v[72:73], v[72:73], v[74:75]
	v_exp_f32_e32 v74, v76
	v_mfma_f32_32x32x16_bf16 v[34:49], v[158:161], v[66:69], v[34:49]
	v_exp_f32_e32 v75, v77
	v_exp_f32_e32 v76, v80
	v_exp_f32_e32 v77, v81
	v_cvt_f32_ubyte3_e32 v79, v210
	v_cvt_f32_ubyte2_e32 v78, v210
	v_pk_mul_f32 v[74:75], v[74:75], v[78:79]
	s_cmp_lt_i32 s56, 26
	v_mfma_f32_32x32x16_bf16 v[50:65], v[154:157], v[66:69], v[50:65]
	v_cvt_f32_ubyte3_e32 v67, v211
	v_cvt_f32_ubyte2_e32 v66, v211
	v_mul_f32_e64 v76, v76, v66
	v_mul_f32_e64 v77, v77, v67
	v_cvt_pk_bf16_f32 v66, v70, v71
	v_cvt_pk_bf16_f32 v67, v74, v75
	v_cvt_pk_bf16_f32 v68, v72, v73
	v_cvt_pk_bf16_f32 v69, v76, v77
	s_cselect_b64 s[4:5], -1, 0
	s_cmp_lt_i32 s24, 10
	v_mfma_f32_32x32x16_bf16 v[18:33], v[166:169], v[66:69], v[18:33]
	s_cselect_b64 s[0:1], -1, 0
	s_or_b64 s[4:5], s[4:5], s[0:1]
	s_and_b64 vcc, exec, s[4:5]
	v_mfma_f32_32x32x16_bf16 v[34:49], v[170:173], v[66:69], v[34:49]
	v_mfma_f32_32x32x16_bf16 v[50:65], v[154:157], v[66:69], v[50:65]
	s_cbranch_vccz .LBB0_533

; __device__ __forceinline__ void gmlp_unit(const GmlpP& P, int b, int ch, LAS unsigned char* lds, int wave, int lane_in) {
;     ...
;             for (int i = 0; i < 8; ++i) {
;                 const u32x4 raw = rawv[8 * hf + i];
;                 float v[8];
; #pragma unroll
;                 for (int j = 0; j < 4; ++j) { v[2 * j] = __builtin_bit_cast(float, raw[j] << 16); v[2 * j + 1] = __builtin_bit_cast(float, raw[j] & 0xffff0000u); }
;                 float sm = 0.f;
; #pragma unroll
;                 for (int j = 0; j < 8; ++j) sm += v[j];
;                 sm = row16_sum(sm);
;                 const float mu = sm * (1.0f / 128.0f);
;                 float sq = 0.f;
; #pragma unroll
;                 for (int j = 0; j < 8; ++j) { v[j] -= mu; sq += v[j] * v[j]; }
;                 sq = row16_sum(sq);
;                 const float rs = __builtin_amdgcn_rsqf(sq * (1.0f / 128.0f) + EPS);
; #pragma unroll
;                 for (int j = 0; j < 8; ++j) yv[j][i] = v[j] * rs * (j < 4 ? ga0[j & 3] : ga1[j & 3]) + (j < 4 ? be0[j & 3] : be1[j & 3]);
.LBB0_541:
	s_or_b64 exec, exec, s[26:27]
	v_add_u32_e32 v109, s20, v86
	s_waitcnt vmcnt(14)
	v_lshlrev_b32_e32 v87, 16, v78
	v_lshlrev_b32_e32 v86, 16, v74
	s_waitcnt vmcnt(0)
	v_and_b32_e32 v82, 0xffff0000, v77
	v_lshlrev_b32_e32 v85, 16, v81
	v_lshlrev_b32_e32 v84, 16, v77
	v_and_b32_e32 v83, 0xffff0000, v81
	v_and_b32_e32 v89, 0xffff0000, v78
	v_and_b32_e32 v88, 0xffff0000, v74
	v_lshlrev_b32_e32 v90, 16, v75
	v_and_b32_e32 v78, 0xffff0000, v75
	v_lshlrev_b32_e32 v75, 16, v80
	v_and_b32_e32 v77, 0xffff0000, v80
	v_pk_add_f32 v[80:81], v[86:87], 0 op_sel_hi:[1,0]
	v_lshlrev_b32_e32 v91, 16, v79
	v_pk_add_f32 v[80:81], v[80:81], v[88:89]
	v_and_b32_e32 v79, 0xffff0000, v79
	v_pk_add_f32 v[80:81], v[80:81], v[90:91]
	v_lshlrev_b32_e32 v74, 16, v76
	v_pk_add_f32 v[80:81], v[80:81], v[78:79]
	v_and_b32_e32 v76, 0xffff0000, v76
	v_pk_add_f32 v[80:81], v[80:81], v[74:75]
	v_mov_b32_e32 v98, v82
	v_pk_add_f32 v[80:81], v[80:81], v[76:77]
	v_mov_b32_e32 v99, v84
	v_pk_add_f32 v[80:81], v[80:81], v[84:85]
	v_mov_b32_e32 v84, v83
	v_pk_add_f32 v[80:81], v[80:81], v[82:83]
	v_mov_b32_e32 v94, v76
	v_mov_b32_e32 v95, v74
	v_mov_b32_dpp v92, v80 row_ror:8 row_mask:0xf bank_mask:0xf bound_ctrl:1
	v_mov_b32_dpp v93, v81 row_ror:8 row_mask:0xf bank_mask:0xf bound_ctrl:1
	v_pk_add_f32 v[80:81], v[80:81], v[92:93]
	v_mov_b32_e32 v74, v77
	v_lshlrev_b32_e32 v106, 3, v108
	v_mov_b32_dpp v92, v80 row_ror:4 row_mask:0xf bank_mask:0xf bound_ctrl:1
	v_mov_b32_dpp v93, v81 row_ror:4 row_mask:0xf bank_mask:0xf bound_ctrl:1
	v_pk_add_f32 v[80:81], v[80:81], v[92:93]
	v_lshlrev_b32_e32 v107, 16, v71
	v_and_b32_e32 v71, 0xffff0000, v71
	v_mov_b32_dpp v92, v80 quad_perm:[2,3,0,1] row_mask:0xf bank_mask:0xf bound_ctrl:1
	v_mov_b32_dpp v93, v81 quad_perm:[2,3,0,1] row_mask:0xf bank_mask:0xf bound_ctrl:1
	v_pk_add_f32 v[80:81], v[80:81], v[92:93]
	v_lshlrev_b32_e32 v124, 16, v63
	v_lshlrev_b32_e32 v125, 16, v59
	v_mov_b32_dpp v92, v80 quad_perm:[1,0,3,2] row_mask:0xf bank_mask:0xf bound_ctrl:1
	v_mov_b32_dpp v93, v81 quad_perm:[1,0,3,2] row_mask:0xf bank_mask:0xf bound_ctrl:1
	v_pk_add_f32 v[80:81], v[80:81], v[92:93]
	v_and_b32_e32 v59, 0xffff0000, v59
	v_pk_mul_f32 v[92:93], v[80:81], s[24:25] op_sel_hi:[1,0]
	v_pk_fma_f32 v[82:83], v[80:81], s[24:25], v[88:89] op_sel_hi:[1,0,1] neg_lo:[1,0,0] neg_hi:[1,0,0]
	v_pk_fma_f32 v[86:87], v[80:81], s[24:25], v[86:87] op_sel_hi:[1,0,1] neg_lo:[1,0,0] neg_hi:[1,0,0]
	v_pk_add_f32 v[104:105], v[84:85], v[92:93] op_sel:[0,1] neg_lo:[0,1] neg_hi:[0,1]
	v_pk_mul_f32 v[84:85], v[82:83], v[82:83]
	v_pk_fma_f32 v[88:89], v[80:81], s[24:25], v[90:91] op_sel_hi:[1,0,1] neg_lo:[1,0,0] neg_hi:[1,0,0]
	v_pk_fma_f32 v[84:85], v[86:87], v[86:87], v[84:85]
	v_pk_add_f32 v[96:97], v[94:95], v[92:93] op_sel_hi:[1,0] neg_lo:[0,1] neg_hi:[0,1]
	v_pk_add_f32 v[102:103], v[74:75], v[92:93] op_sel:[0,1] neg_lo:[0,1] neg_hi:[0,1]
	v_pk_fma_f32 v[84:85], v[88:89], v[88:89], v[84:85]
	v_pk_fma_f32 v[78:79], v[80:81], s[24:25], v[78:79] op_sel_hi:[1,0,1] neg_lo:[1,0,0] neg_hi:[1,0,0]
	v_pk_mul_f32 v[94:95], v[96:97], v[96:97]
	v_pk_mul_f32 v[74:75], v[102:103], v[102:103]
	v_pk_fma_f32 v[80:81], v[78:79], v[78:79], v[84:85]
	v_pk_add_f32 v[98:99], v[98:99], v[92:93] op_sel_hi:[1,0] neg_lo:[0,1] neg_hi:[0,1]
	v_add_f32_e32 v80, v95, v80
	v_add_f32_e32 v75, v75, v81
	v_pk_mul_f32 v[100:101], v[98:99], v[98:99]
	v_pk_mul_f32 v[76:77], v[104:105], v[104:105]
	v_add_f32_e32 v80, v94, v80
	v_add_f32_e32 v74, v74, v75
	v_add_f32_e32 v80, v101, v80
	v_add_f32_e32 v74, v77, v74
	v_add_f32_e32 v80, v100, v80
	v_add_f32_e32 v74, v76, v74
	v_and_b32_e32 v154, 31, v139
	v_add_f32_dpp v80, v80, v80 row_ror:8 row_mask:0xf bank_mask:0xf bound_ctrl:1
	v_add_f32_dpp v74, v74, v74 row_ror:8 row_mask:0xf bank_mask:0xf bound_ctrl:1
	v_ashrrev_i32_e32 v140, 5, v139
	v_add_f32_dpp v80, v80, v80 row_ror:4 row_mask:0xf bank_mask:0xf bound_ctrl:1
	v_add_f32_dpp v74, v74, v74 row_ror:4 row_mask:0xf bank_mask:0xf bound_ctrl:1
	v_bfe_u32 v188, v139, 3, 2
	v_add_f32_dpp v80, v80, v80 quad_perm:[2,3,0,1] row_mask:0xf bank_mask:0xf bound_ctrl:1
	v_add_f32_dpp v74, v74, v74 quad_perm:[2,3,0,1] row_mask:0xf bank_mask:0xf bound_ctrl:1
	v_add_u32_e32 v152, 2, v140
	v_add_f32_dpp v80, v80, v80 quad_perm:[1,0,3,2] row_mask:0xf bank_mask:0xf bound_ctrl:1
	v_add_f32_dpp v74, v74, v74 quad_perm:[1,0,3,2] row_mask:0xf bank_mask:0xf bound_ctrl:1
	v_fmamk_f32 v80, v80, 0x3c000000, v1
	v_fmamk_f32 v74, v74, 0x3c000000, v1
	v_rsq_f32_e32 v100, v80
	v_rsq_f32_e32 v101, v74
	v_or_b32_e32 v74, s6, v106
	v_mul_lo_u32 v74, v74, s48
	v_add_u32_e32 v75, 0, v74
	v_pk_mul_f32 v[76:77], v[86:87], v[100:101]
	v_pk_mul_f32 v[78:79], v[78:79], v[100:101]
	v_pk_fma_f32 v[94:95], v[10:11], v[76:77], v[14:15] op_sel_hi:[0,1,0]
	v_pk_mul_f32 v[76:77], v[82:83], v[100:101]
	v_mov_b32_e32 v74, v13
	v_pk_fma_f32 v[92:93], v[10:11], v[76:77], v[14:15] op_sel:[1,0,1]
	v_pk_mul_f32 v[76:77], v[88:89], v[100:101]
	v_mov_b32_e32 v80, v7
	v_pk_fma_f32 v[90:91], v[12:13], v[76:77], v[16:17] op_sel_hi:[0,1,0]
	v_mov_b32_e32 v76, v17
	v_pk_fma_f32 v[88:89], v[74:75], v[78:79], v[76:77] op_sel_hi:[0,1,0]
	v_mov_b32_e32 v78, v97
	v_mov_b32_e32 v79, v103
	v_pk_mul_f32 v[78:79], v[78:79], v[100:101]
	v_mov_b32_e32 v97, v102
	v_pk_fma_f32 v[86:87], v[2:3], v[78:79], v[6:7] op_sel_hi:[0,1,0]
	v_pk_mul_f32 v[82:83], v[96:97], v[100:101]
	v_mov_b32_e32 v78, v3
	v_pk_fma_f32 v[84:85], v[78:79], v[82:83], v[80:81] op_sel_hi:[0,1,0]
	v_mov_b32_e32 v82, v99
	v_mov_b32_e32 v83, v105
	v_mov_b32_e32 v99, v104
	v_lshlrev_b32_e32 v103, 16, v70
	v_lshlrev_b32_e32 v102, 16, v66
	v_pk_mul_f32 v[82:83], v[82:83], v[100:101]
; __device__ __forceinline__ void gmlp_unit(const GmlpP& P, int b, int ch, LAS unsigned char* lds, int wave, int lane_in) {
;     ...
;             for (int i = 0; i < 8; ++i) {
;                 const u32x4 raw = rawv[8 * hf + i];
;                 float v[8];
; #pragma unroll
;                 for (int j = 0; j < 4; ++j) { v[2 * j] = __builtin_bit_cast(float, raw[j] << 16); v[2 * j + 1] = __builtin_bit_cast(float, raw[j] & 0xffff0000u); }
;                 float sm = 0.f;
; #pragma unroll
;                 for (int j = 0; j < 8; ++j) sm += v[j];
;                 sm = row16_sum(sm);
;                 const float mu = sm * (1.0f / 128.0f);
;                 float sq = 0.f;
; #pragma unroll
;                 for (int j = 0; j < 8; ++j) { v[j] -= mu; sq += v[j] * v[j]; }
;                 sq = row16_sum(sq);
;                 const float rs = __builtin_amdgcn_rsqf(sq * (1.0f / 128.0f) + EPS);
; #pragma unroll
;                 for (int j = 0; j < 8; ++j) yv[j][i] = v[j] * rs * (j < 4 ? ga0[j & 3] : ga1[j & 3]) + (j < 4 ? be0[j & 3] : be1[j & 3]);
	v_pk_mul_f32 v[96:97], v[98:99], v[100:101]
	v_and_b32_e32 v98, 0xffff0000, v69
	v_lshlrev_b32_e32 v101, 16, v73
	v_lshlrev_b32_e32 v100, 16, v69
	v_and_b32_e32 v99, 0xffff0000, v73
	v_and_b32_e32 v105, 0xffff0000, v70
	v_and_b32_e32 v104, 0xffff0000, v66
	v_lshlrev_b32_e32 v106, 16, v67
	v_and_b32_e32 v70, 0xffff0000, v67
	v_lshlrev_b32_e32 v67, 16, v72
	v_and_b32_e32 v69, 0xffff0000, v72
	v_pk_add_f32 v[72:73], v[102:103], 0 op_sel_hi:[1,0]
	v_lshlrev_b32_e32 v66, 16, v68
	v_pk_add_f32 v[72:73], v[72:73], v[104:105]
	v_and_b32_e32 v68, 0xffff0000, v68
	v_pk_add_f32 v[72:73], v[72:73], v[106:107]
	v_mov_b32_e32 v112, v68
	v_pk_add_f32 v[72:73], v[72:73], v[70:71]
	v_mov_b32_e32 v113, v66
	v_pk_add_f32 v[72:73], v[72:73], v[66:67]
	v_mov_b32_e32 v116, v98
	v_pk_add_f32 v[72:73], v[72:73], v[68:69]
	v_mov_b32_e32 v117, v100
	v_pk_add_f32 v[72:73], v[72:73], v[100:101]
	v_mov_b32_e32 v66, v69
	v_pk_add_f32 v[72:73], v[72:73], v[98:99]
	v_mov_b32_e32 v100, v99
	v_pk_fma_f32 v[82:83], v[4:5], v[82:83], v[8:9] op_sel_hi:[0,1,0]
	v_mov_b32_dpp v110, v72 row_ror:8 row_mask:0xf bank_mask:0xf bound_ctrl:1
	v_mov_b32_dpp v111, v73 row_ror:8 row_mask:0xf bank_mask:0xf bound_ctrl:1
	v_pk_add_f32 v[72:73], v[72:73], v[110:111]
	v_xor_b32_e32 v153, v188, v152
	v_cmp_gt_u32_e32 vcc, 32, v139
	v_mov_b32_dpp v110, v72 row_ror:4 row_mask:0xf bank_mask:0xf bound_ctrl:1
	v_mov_b32_dpp v111, v73 row_ror:4 row_mask:0xf bank_mask:0xf bound_ctrl:1
	v_pk_add_f32 v[72:73], v[72:73], v[110:111]
	s_nop 1
	v_mov_b32_dpp v110, v72 quad_perm:[2,3,0,1] row_mask:0xf bank_mask:0xf bound_ctrl:1
	v_mov_b32_dpp v111, v73 quad_perm:[2,3,0,1] row_mask:0xf bank_mask:0xf bound_ctrl:1
	v_pk_add_f32 v[72:73], v[72:73], v[110:111]
	s_nop 1
	v_mov_b32_dpp v110, v72 quad_perm:[1,0,3,2] row_mask:0xf bank_mask:0xf bound_ctrl:1
	v_mov_b32_dpp v111, v73 quad_perm:[1,0,3,2] row_mask:0xf bank_mask:0xf bound_ctrl:1
	v_pk_add_f32 v[72:73], v[72:73], v[110:111]
	s_nop 0
	v_pk_mul_f32 v[110:111], v[72:73], s[24:25] op_sel_hi:[1,0]
	v_pk_fma_f32 v[98:99], v[72:73], s[24:25], v[104:105] op_sel_hi:[1,0,1] neg_lo:[1,0,0] neg_hi:[1,0,0]
	v_pk_fma_f32 v[102:103], v[72:73], s[24:25], v[102:103] op_sel_hi:[1,0,1] neg_lo:[1,0,0] neg_hi:[1,0,0]
	v_pk_add_f32 v[112:113], v[112:113], v[110:111] op_sel_hi:[1,0] neg_lo:[0,1] neg_hi:[0,1]
	v_pk_add_f32 v[116:117], v[116:117], v[110:111] op_sel_hi:[1,0] neg_lo:[0,1] neg_hi:[0,1]
	v_pk_add_f32 v[120:121], v[66:67], v[110:111] op_sel:[0,1] neg_lo:[0,1] neg_hi:[0,1]
	v_pk_add_f32 v[110:111], v[100:101], v[110:111] op_sel:[0,1] neg_lo:[0,1] neg_hi:[0,1]
	v_pk_mul_f32 v[100:101], v[98:99], v[98:99]
	v_pk_fma_f32 v[122:123], v[72:73], s[24:25], v[106:107] op_sel_hi:[1,0,1] neg_lo:[1,0,0] neg_hi:[1,0,0]
	v_pk_fma_f32 v[100:101], v[102:103], v[102:103], v[100:101]
	v_pk_fma_f32 v[72:73], v[72:73], s[24:25], v[70:71] op_sel_hi:[1,0,1] neg_lo:[1,0,0] neg_hi:[1,0,0]
	v_pk_fma_f32 v[100:101], v[122:123], v[122:123], v[100:101]
	v_pk_mul_f32 v[114:115], v[112:113], v[112:113]
	v_pk_fma_f32 v[70:71], v[72:73], v[72:73], v[100:101]
	v_pk_mul_f32 v[118:119], v[116:117], v[116:117]
	v_add_f32_e32 v3, v115, v70
	v_add_f32_e32 v3, v114, v3
	v_add_f32_e32 v3, v119, v3
	v_add_f32_e32 v3, v118, v3
	v_pk_mul_f32 v[66:67], v[120:121], v[120:121]
	v_pk_mul_f32 v[68:69], v[110:111], v[110:111]
	v_add_f32_dpp v3, v3, v3 row_ror:8 row_mask:0xf bank_mask:0xf bound_ctrl:1
	v_lshlrev_b32_e32 v119, 16, v61
	v_lshlrev_b32_e32 v118, 16, v65
	v_add_f32_dpp v3, v3, v3 row_ror:4 row_mask:0xf bank_mask:0xf bound_ctrl:1
	v_mov_b32_e32 v133, v118
	s_nop 0
	v_add_f32_dpp v3, v3, v3 quad_perm:[2,3,0,1] row_mask:0xf bank_mask:0xf bound_ctrl:1
	s_nop 1
	v_add_f32_dpp v3, v3, v3 quad_perm:[1,0,3,2] row_mask:0xf bank_mask:0xf bound_ctrl:1
	v_fmamk_f32 v3, v3, 0x3c000000, v1
	v_rsq_f32_e32 v114, v3
	v_add_f32_e32 v3, v67, v71
	v_add_f32_e32 v3, v66, v3
	v_add_f32_e32 v3, v69, v3
	v_add_f32_e32 v3, v68, v3
	v_mov_b32_e32 v66, v5
	v_mov_b32_e32 v68, v9
	v_add_f32_dpp v3, v3, v3 row_ror:8 row_mask:0xf bank_mask:0xf bound_ctrl:1
	v_pk_fma_f32 v[70:71], v[66:67], v[96:97], v[68:69] op_sel_hi:[0,1,0]
	s_nop 0
	v_add_f32_dpp v3, v3, v3 row_ror:4 row_mask:0xf bank_mask:0xf bound_ctrl:1
	s_nop 1
	v_add_f32_dpp v3, v3, v3 quad_perm:[2,3,0,1] row_mask:0xf bank_mask:0xf bound_ctrl:1
	s_nop 1
	v_add_f32_dpp v3, v3, v3 quad_perm:[1,0,3,2] row_mask:0xf bank_mask:0xf bound_ctrl:1
	v_fmamk_f32 v3, v3, 0x3c000000, v1
	v_rsq_f32_e32 v115, v3
	s_nop 0
	v_pk_mul_f32 v[72:73], v[72:73], v[114:115]
	v_pk_mul_f32 v[96:97], v[102:103], v[114:115]
	v_pk_fma_f32 v[100:101], v[74:75], v[72:73], v[76:77] op_sel_hi:[0,1,0]
	v_mov_b32_e32 v72, v113
	v_mov_b32_e32 v73, v121
	v_pk_fma_f32 v[106:107], v[10:11], v[96:97], v[14:15] op_sel_hi:[0,1,0]
	v_pk_mul_f32 v[96:97], v[98:99], v[114:115]
	v_pk_mul_f32 v[72:73], v[72:73], v[114:115]
	v_mov_b32_e32 v113, v120
	v_lshlrev_b32_e32 v121, 16, v58
	v_lshlrev_b32_e32 v120, 16, v62
	v_pk_fma_f32 v[104:105], v[10:11], v[96:97], v[14:15] op_sel:[1,0,1]
	v_pk_mul_f32 v[96:97], v[122:123], v[114:115]
	v_pk_fma_f32 v[98:99], v[2:3], v[72:73], v[6:7] op_sel_hi:[0,1,0]
	v_pk_mul_f32 v[72:73], v[112:113], v[114:115]
	v_and_b32_e32 v112, 0xffff0000, v65
	v_and_b32_e32 v113, 0xffff0000, v61
	v_and_b32_e32 v123, 0xffff0000, v58
	v_and_b32_e32 v122, 0xffff0000, v62
	v_and_b32_e32 v58, 0xffff0000, v63
	v_lshlrev_b32_e32 v63, 16, v60
	v_lshlrev_b32_e32 v62, 16, v64
	v_and_b32_e32 v61, 0xffff0000, v60
	v_and_b32_e32 v60, 0xffff0000, v64
	v_pk_add_f32 v[64:65], v[120:121], 0 op_sel_hi:[1,0]
	v_mov_b32_e32 v128, v60
	v_pk_add_f32 v[64:65], v[64:65], v[122:123]
	v_mov_b32_e32 v129, v62
; __device__ __forceinline__ void gmlp_unit(const GmlpP& P, int b, int ch, LAS unsigned char* lds, int wave, int lane_in) {
;     ...
;             for (int i = 0; i < 8; ++i) {
;                 const u32x4 raw = rawv[8 * hf + i];
;                 float v[8];
; #pragma unroll
;                 for (int j = 0; j < 4; ++j) { v[2 * j] = __builtin_bit_cast(float, raw[j] << 16); v[2 * j + 1] = __builtin_bit_cast(float, raw[j] & 0xffff0000u); }
;                 float sm = 0.f;
; #pragma unroll
;                 for (int j = 0; j < 8; ++j) sm += v[j];
;                 sm = row16_sum(sm);
;                 const float mu = sm * (1.0f / 128.0f);
;                 float sq = 0.f;
; #pragma unroll
;                 for (int j = 0; j < 8; ++j) { v[j] -= mu; sq += v[j] * v[j]; }
;                 sq = row16_sum(sq);
;                 const float rs = __builtin_amdgcn_rsqf(sq * (1.0f / 128.0f) + EPS);
; #pragma unroll
;                 for (int j = 0; j < 8; ++j) yv[j][i] = v[j] * rs * (j < 4 ? ga0[j & 3] : ga1[j & 3]) + (j < 4 ? be0[j & 3] : be1[j & 3]);
	v_pk_add_f32 v[64:65], v[64:65], v[124:125]
	v_mov_b32_e32 v132, v112
	v_pk_add_f32 v[64:65], v[64:65], v[58:59]
	v_pk_fma_f32 v[102:103], v[12:13], v[96:97], v[16:17] op_sel_hi:[0,1,0]
	v_pk_add_f32 v[64:65], v[64:65], v[62:63]
	v_mov_b32_e32 v62, v61
	v_pk_add_f32 v[64:65], v[64:65], v[60:61]
	v_pk_fma_f32 v[96:97], v[78:79], v[72:73], v[80:81] op_sel_hi:[0,1,0]
	v_pk_add_f32 v[64:65], v[64:65], v[118:119]
	v_mov_b32_e32 v118, v113
	v_pk_add_f32 v[64:65], v[64:65], v[112:113]
	v_mov_b32_e32 v72, v117
	v_mov_b32_e32 v73, v111
	v_mov_b32_dpp v126, v64 row_ror:8 row_mask:0xf bank_mask:0xf bound_ctrl:1
	v_mov_b32_dpp v127, v65 row_ror:8 row_mask:0xf bank_mask:0xf bound_ctrl:1
	v_pk_add_f32 v[64:65], v[64:65], v[126:127]
	v_mov_b32_e32 v117, v110
	v_pk_mul_f32 v[72:73], v[72:73], v[114:115]
	v_mov_b32_dpp v126, v64 row_ror:4 row_mask:0xf bank_mask:0xf bound_ctrl:1
	v_mov_b32_dpp v127, v65 row_ror:4 row_mask:0xf bank_mask:0xf bound_ctrl:1
	v_pk_add_f32 v[64:65], v[64:65], v[126:127]
	v_pk_fma_f32 v[72:73], v[4:5], v[72:73], v[8:9] op_sel_hi:[0,1,0]
	s_nop 0
	v_mov_b32_dpp v126, v64 quad_perm:[2,3,0,1] row_mask:0xf bank_mask:0xf bound_ctrl:1
	v_mov_b32_dpp v127, v65 quad_perm:[2,3,0,1] row_mask:0xf bank_mask:0xf bound_ctrl:1
	v_pk_add_f32 v[64:65], v[64:65], v[126:127]
	s_nop 1
	v_mov_b32_dpp v126, v64 quad_perm:[1,0,3,2] row_mask:0xf bank_mask:0xf bound_ctrl:1
	v_mov_b32_dpp v127, v65 quad_perm:[1,0,3,2] row_mask:0xf bank_mask:0xf bound_ctrl:1
	v_pk_add_f32 v[64:65], v[64:65], v[126:127]
	s_nop 0
	v_pk_mul_f32 v[126:127], v[64:65], s[24:25] op_sel_hi:[1,0]
	v_pk_fma_f32 v[122:123], v[64:65], s[24:25], v[122:123] op_sel_hi:[1,0,1] neg_lo:[1,0,0] neg_hi:[1,0,0]
	v_pk_fma_f32 v[120:121], v[64:65], s[24:25], v[120:121] op_sel_hi:[1,0,1] neg_lo:[1,0,0] neg_hi:[1,0,0]
	v_pk_add_f32 v[128:129], v[128:129], v[126:127] op_sel_hi:[1,0] neg_lo:[0,1] neg_hi:[0,1]
	v_pk_add_f32 v[132:133], v[132:133], v[126:127] op_sel_hi:[1,0] neg_lo:[0,1] neg_hi:[0,1]
	v_pk_add_f32 v[60:61], v[62:63], v[126:127] op_sel:[0,1] neg_lo:[0,1] neg_hi:[0,1]
	v_pk_add_f32 v[112:113], v[118:119], v[126:127] op_sel:[0,1] neg_lo:[0,1] neg_hi:[0,1]
	v_pk_mul_f32 v[126:127], v[122:123], v[122:123]
	v_pk_fma_f32 v[124:125], v[64:65], s[24:25], v[124:125] op_sel_hi:[1,0,1] neg_lo:[1,0,0] neg_hi:[1,0,0]
	v_pk_fma_f32 v[126:127], v[120:121], v[120:121], v[126:127]
	v_pk_fma_f32 v[58:59], v[64:65], s[24:25], v[58:59] op_sel_hi:[1,0,1] neg_lo:[1,0,0] neg_hi:[1,0,0]
	v_pk_fma_f32 v[126:127], v[124:125], v[124:125], v[126:127]
	v_pk_mul_f32 v[130:131], v[128:129], v[128:129]
	v_pk_fma_f32 v[64:65], v[58:59], v[58:59], v[126:127]
	v_pk_mul_f32 v[134:135], v[132:133], v[132:133]
	v_add_f32_e32 v3, v131, v64
	v_add_f32_e32 v3, v130, v3
	v_add_f32_e32 v3, v135, v3
	v_add_f32_e32 v3, v134, v3
	v_pk_mul_f32 v[62:63], v[60:61], v[60:61]
	v_pk_mul_f32 v[118:119], v[112:113], v[112:113]
	v_add_f32_dpp v3, v3, v3 row_ror:8 row_mask:0xf bank_mask:0xf bound_ctrl:1
	v_lshlrev_b32_e32 v127, 16, v54
	v_lshlrev_b32_e32 v126, 16, v50
	v_add_f32_dpp v3, v3, v3 row_ror:4 row_mask:0xf bank_mask:0xf bound_ctrl:1
	v_lshlrev_b32_e32 v130, 16, v51
	v_lshlrev_b32_e32 v131, 16, v55
	v_add_f32_dpp v3, v3, v3 quad_perm:[2,3,0,1] row_mask:0xf bank_mask:0xf bound_ctrl:1
	v_and_b32_e32 v55, 0xffff0000, v55
	s_nop 0
	v_add_f32_dpp v3, v3, v3 quad_perm:[1,0,3,2] row_mask:0xf bank_mask:0xf bound_ctrl:1
	v_fmamk_f32 v3, v3, 0x3c000000, v1
	v_rsq_f32_e32 v64, v3
	v_add_f32_e32 v3, v63, v65
	v_add_f32_e32 v3, v62, v3
	v_add_f32_e32 v3, v119, v3
	v_add_f32_e32 v3, v118, v3
	v_mov_b32_e32 v118, v129
	v_mov_b32_e32 v129, v60
	v_add_f32_dpp v3, v3, v3 row_ror:8 row_mask:0xf bank_mask:0xf bound_ctrl:1
	v_pk_mul_f32 v[62:63], v[116:117], v[114:115]
	v_mov_b32_e32 v119, v61
	v_add_f32_dpp v3, v3, v3 row_ror:4 row_mask:0xf bank_mask:0xf bound_ctrl:1
	v_pk_fma_f32 v[62:63], v[66:67], v[62:63], v[68:69] op_sel_hi:[0,1,0]
	s_nop 0
	v_add_f32_dpp v3, v3, v3 quad_perm:[2,3,0,1] row_mask:0xf bank_mask:0xf bound_ctrl:1
	s_nop 1
	v_add_f32_dpp v3, v3, v3 quad_perm:[1,0,3,2] row_mask:0xf bank_mask:0xf bound_ctrl:1
	v_fmamk_f32 v3, v3, 0x3c000000, v1
	v_rsq_f32_e32 v65, v3
	s_nop 0
	v_pk_mul_f32 v[114:115], v[122:123], v[64:65]
	v_pk_mul_f32 v[116:117], v[124:125], v[64:65]
	v_pk_mul_f32 v[60:61], v[128:129], v[64:65]
	v_and_b32_e32 v122, 0xffff0000, v53
	v_lshlrev_b32_e32 v125, 16, v57
	v_lshlrev_b32_e32 v124, 16, v53
	v_and_b32_e32 v123, 0xffff0000, v57
	v_and_b32_e32 v129, 0xffff0000, v54
	v_and_b32_e32 v128, 0xffff0000, v50
	v_and_b32_e32 v54, 0xffff0000, v51
	v_lshlrev_b32_e32 v51, 16, v56
	v_and_b32_e32 v53, 0xffff0000, v56
	v_pk_add_f32 v[56:57], v[126:127], 0 op_sel_hi:[1,0]
	v_lshlrev_b32_e32 v50, 16, v52
	v_pk_add_f32 v[56:57], v[56:57], v[128:129]
	v_and_b32_e32 v52, 0xffff0000, v52
	v_pk_add_f32 v[56:57], v[56:57], v[130:131]
	v_mov_b32_e32 v136, v52
	v_pk_add_f32 v[56:57], v[56:57], v[54:55]
	v_mov_b32_e32 v137, v50
	v_pk_add_f32 v[56:57], v[56:57], v[50:51]
	v_mov_b32_e32 v146, v122
	v_pk_add_f32 v[56:57], v[56:57], v[52:53]
	v_mov_b32_e32 v147, v124
	v_pk_add_f32 v[56:57], v[56:57], v[124:125]
	v_mov_b32_e32 v50, v53
	v_pk_add_f32 v[56:57], v[56:57], v[122:123]
	v_mov_b32_e32 v124, v123
	v_pk_mul_f32 v[118:119], v[118:119], v[64:65]
	v_mov_b32_dpp v134, v56 row_ror:8 row_mask:0xf bank_mask:0xf bound_ctrl:1
	v_mov_b32_dpp v135, v57 row_ror:8 row_mask:0xf bank_mask:0xf bound_ctrl:1
	v_pk_add_f32 v[56:57], v[56:57], v[134:135]
	v_pk_fma_f32 v[118:119], v[2:3], v[118:119], v[6:7] op_sel_hi:[0,1,0]
	v_pk_mul_f32 v[110:111], v[120:121], v[64:65]
	v_mov_b32_dpp v134, v56 row_ror:4 row_mask:0xf bank_mask:0xf bound_ctrl:1
; #define LAS __attribute__((address_space(3)))
; __device__ __forceinline__ unsigned pk2(float lo, float hi) { f32x2 v = {lo, hi}; bf16x2_t b = __builtin_convertvector(v, bf16x2_t); return __builtin_bit_cast(unsigned, b); }
; __device__ __forceinline__ void gmlp_unit(const GmlpP& P, int b, int ch, LAS unsigned char* lds, int wave, int lane_in) {
;     ...
;             for (int i = 0; i < 8; ++i) {
;                 const u32x4 raw = rawv[8 * hf + i];
;                 float v[8];
; #pragma unroll
;                 for (int j = 0; j < 4; ++j) { v[2 * j] = __builtin_bit_cast(float, raw[j] << 16); v[2 * j + 1] = __builtin_bit_cast(float, raw[j] & 0xffff0000u); }
;                 float sm = 0.f;
; #pragma unroll
;                 for (int j = 0; j < 8; ++j) sm += v[j];
;                 sm = row16_sum(sm);
;                 const float mu = sm * (1.0f / 128.0f);
;                 float sq = 0.f;
; #pragma unroll
;                 for (int j = 0; j < 8; ++j) { v[j] -= mu; sq += v[j] * v[j]; }
;                 sq = row16_sum(sq);
;                 const float rs = __builtin_amdgcn_rsqf(sq * (1.0f / 128.0f) + EPS);
; #pragma unroll
;                 for (int j = 0; j < 8; ++j) yv[j][i] = v[j] * rs * (j < 4 ? ga0[j & 3] : ga1[j & 3]) + (j < 4 ? be0[j & 3] : be1[j & 3]);
;             }
;             const int s0 = 64 * th + 16 * rr + 8 * hf;
;             LAS unsigned char* dst = lds + (gI * 128 + 8 * sub) * LDS_TT_PITCH + 16 * ((s0 >> 3) ^ sub);
; #pragma unroll
;             for (int j = 0; j < 8; ++j) {
;                 u32x4 w; w.x = pk2(yv[j][0], yv[j][1]); w.y = pk2(yv[j][2], yv[j][3]); w.z = pk2(yv[j][4], yv[j][5]); w.w = pk2(yv[j][6], yv[j][7]);
;                 *(LAS u32x4*)(dst + j * LDS_TT_PITCH) = w;
;             }
	v_mov_b32_dpp v135, v57 row_ror:4 row_mask:0xf bank_mask:0xf bound_ctrl:1
	v_pk_add_f32 v[56:57], v[56:57], v[134:135]
	v_mov_b32_e32 v120, v133
	v_mov_b32_e32 v133, v112
	v_mov_b32_dpp v134, v56 quad_perm:[2,3,0,1] row_mask:0xf bank_mask:0xf bound_ctrl:1
	v_mov_b32_dpp v135, v57 quad_perm:[2,3,0,1] row_mask:0xf bank_mask:0xf bound_ctrl:1
	v_pk_add_f32 v[56:57], v[56:57], v[134:135]
	v_mov_b32_e32 v121, v113
	v_pk_mul_f32 v[58:59], v[58:59], v[64:65]
	v_mov_b32_dpp v134, v56 quad_perm:[1,0,3,2] row_mask:0xf bank_mask:0xf bound_ctrl:1
	v_mov_b32_dpp v135, v57 quad_perm:[1,0,3,2] row_mask:0xf bank_mask:0xf bound_ctrl:1
	v_pk_add_f32 v[56:57], v[56:57], v[134:135]
	v_pk_mul_f32 v[120:121], v[120:121], v[64:65]
	v_pk_mul_f32 v[134:135], v[56:57], s[24:25] op_sel_hi:[1,0]
	v_pk_fma_f32 v[128:129], v[56:57], s[24:25], v[128:129] op_sel_hi:[1,0,1] neg_lo:[1,0,0] neg_hi:[1,0,0]
	v_pk_fma_f32 v[126:127], v[56:57], s[24:25], v[126:127] op_sel_hi:[1,0,1] neg_lo:[1,0,0] neg_hi:[1,0,0]
	v_pk_add_f32 v[136:137], v[136:137], v[134:135] op_sel_hi:[1,0] neg_lo:[0,1] neg_hi:[0,1]
	v_pk_add_f32 v[146:147], v[146:147], v[134:135] op_sel_hi:[1,0] neg_lo:[0,1] neg_hi:[0,1]
	v_pk_add_f32 v[50:51], v[50:51], v[134:135] op_sel:[0,1] neg_lo:[0,1] neg_hi:[0,1]
	v_pk_add_f32 v[122:123], v[124:125], v[134:135] op_sel:[0,1] neg_lo:[0,1] neg_hi:[0,1]
	v_pk_mul_f32 v[134:135], v[128:129], v[128:129]
	v_pk_fma_f32 v[130:131], v[56:57], s[24:25], v[130:131] op_sel_hi:[1,0,1] neg_lo:[1,0,0] neg_hi:[1,0,0]
	v_pk_fma_f32 v[134:135], v[126:127], v[126:127], v[134:135]
	v_pk_fma_f32 v[54:55], v[56:57], s[24:25], v[54:55] op_sel_hi:[1,0,1] neg_lo:[1,0,0] neg_hi:[1,0,0]
	v_pk_fma_f32 v[134:135], v[130:131], v[130:131], v[134:135]
	v_pk_mul_f32 v[144:145], v[136:137], v[136:137]
	v_pk_fma_f32 v[56:57], v[54:55], v[54:55], v[134:135]
	v_pk_mul_f32 v[148:149], v[146:147], v[146:147]
	v_add_f32_e32 v3, v145, v56
	v_add_f32_e32 v3, v144, v3
	v_add_f32_e32 v3, v149, v3
	v_add_f32_e32 v3, v148, v3
	v_pk_mul_f32 v[52:53], v[50:51], v[50:51]
	v_pk_mul_f32 v[124:125], v[122:123], v[122:123]
	v_add_f32_dpp v3, v3, v3 row_ror:8 row_mask:0xf bank_mask:0xf bound_ctrl:1
	v_pk_fma_f32 v[110:111], v[10:11], v[110:111], v[14:15] op_sel_hi:[0,1,0]
	v_pk_fma_f32 v[120:121], v[4:5], v[120:121], v[8:9] op_sel_hi:[0,1,0]
	v_add_f32_dpp v3, v3, v3 row_ror:4 row_mask:0xf bank_mask:0xf bound_ctrl:1
	v_pk_fma_f32 v[114:115], v[10:11], v[114:115], v[14:15] op_sel:[1,0,1]
	v_pk_fma_f32 v[116:117], v[12:13], v[116:117], v[16:17] op_sel_hi:[0,1,0]
	v_add_f32_dpp v3, v3, v3 quad_perm:[2,3,0,1] row_mask:0xf bank_mask:0xf bound_ctrl:1
	v_pk_fma_f32 v[58:59], v[74:75], v[58:59], v[76:77] op_sel_hi:[0,1,0]
	v_pk_fma_f32 v[60:61], v[78:79], v[60:61], v[80:81] op_sel_hi:[0,1,0]
	v_add_f32_dpp v3, v3, v3 quad_perm:[1,0,3,2] row_mask:0xf bank_mask:0xf bound_ctrl:1
	v_fmamk_f32 v3, v3, 0x3c000000, v1
	v_rsq_f32_e32 v56, v3
	v_add_f32_e32 v3, v53, v57
	v_add_f32_e32 v3, v52, v3
	v_add_f32_e32 v3, v125, v3
	v_add_f32_e32 v3, v124, v3
	v_pk_mul_f32 v[52:53], v[132:133], v[64:65]
	s_nop 0
	v_add_f32_dpp v3, v3, v3 row_ror:8 row_mask:0xf bank_mask:0xf bound_ctrl:1
	v_pk_fma_f32 v[64:65], v[66:67], v[52:53], v[68:69] op_sel_hi:[0,1,0]
	s_nop 0
	v_add_f32_dpp v3, v3, v3 row_ror:4 row_mask:0xf bank_mask:0xf bound_ctrl:1
	s_nop 1
	v_add_f32_dpp v3, v3, v3 quad_perm:[2,3,0,1] row_mask:0xf bank_mask:0xf bound_ctrl:1
	s_nop 1
	v_add_f32_dpp v3, v3, v3 quad_perm:[1,0,3,2] row_mask:0xf bank_mask:0xf bound_ctrl:1
	v_fmamk_f32 v3, v3, 0x3c000000, v1
	v_rsq_f32_e32 v57, v3
	s_nop 0
	v_pk_mul_f32 v[52:53], v[126:127], v[56:57]
	s_nop 0
	v_pk_fma_f32 v[112:113], v[10:11], v[52:53], v[14:15] op_sel_hi:[0,1,0]
	v_pk_mul_f32 v[52:53], v[128:129], v[56:57]
	s_nop 0
	v_pk_fma_f32 v[124:125], v[10:11], v[52:53], v[14:15] op_sel:[1,0,1]
	v_pk_mul_f32 v[52:53], v[130:131], v[56:57]
	s_nop 0
	v_pk_fma_f32 v[126:127], v[12:13], v[52:53], v[16:17] op_sel_hi:[0,1,0]
	v_pk_mul_f32 v[52:53], v[54:55], v[56:57]
	s_nop 0
	v_pk_fma_f32 v[54:55], v[74:75], v[52:53], v[76:77] op_sel_hi:[0,1,0]
	v_mov_b32_e32 v52, v137
	v_mov_b32_e32 v137, v50
	v_mov_b32_e32 v53, v51
	v_pk_mul_f32 v[50:51], v[136:137], v[56:57]
	v_pk_mul_f32 v[52:53], v[52:53], v[56:57]
	v_pk_fma_f32 v[130:131], v[78:79], v[50:51], v[80:81] op_sel_hi:[0,1,0]
	v_mov_b32_e32 v50, v147
	v_mov_b32_e32 v51, v123
	v_pk_fma_f32 v[128:129], v[2:3], v[52:53], v[6:7] op_sel_hi:[0,1,0]
	v_pk_mul_f32 v[50:51], v[50:51], v[56:57]
	v_mov_b32_e32 v147, v122
	v_ashrrev_i32_e32 v3, 3, v109
	v_pk_fma_f32 v[132:133], v[4:5], v[50:51], v[8:9] op_sel_hi:[0,1,0]
	v_pk_mul_f32 v[50:51], v[146:147], v[56:57]
	v_xor_b32_e32 v5, v3, v108
	v_pk_fma_f32 v[56:57], v[66:67], v[50:51], v[68:69] op_sel_hi:[0,1,0]
	v_lshl_add_u32 v5, v5, 4, v75
	v_cvt_pk_bf16_f32 v50, v94, v95
	v_cvt_pk_bf16_f32 v51, v106, v107
	v_cvt_pk_bf16_f32 v52, v110, v111
	v_cvt_pk_bf16_f32 v53, v112, v113
	ds_write_b128 v5, v[50:53]
	v_cvt_pk_bf16_f32 v50, v92, v93
	v_cvt_pk_bf16_f32 v51, v104, v105
	v_cvt_pk_bf16_f32 v52, v114, v115
	v_cvt_pk_bf16_f32 v53, v124, v125
	ds_write_b128 v5, v[50:53] offset:272
	v_cvt_pk_bf16_f32 v50, v90, v91
	v_cvt_pk_bf16_f32 v51, v102, v103
	v_cvt_pk_bf16_f32 v52, v116, v117
	v_cvt_pk_bf16_f32 v53, v126, v127
	ds_write_b128 v5, v[50:53] offset:544
	v_cvt_pk_bf16_f32 v50, v88, v89
	v_cvt_pk_bf16_f32 v51, v100, v101
	v_cvt_pk_bf16_f32 v52, v58, v59
	v_cvt_pk_bf16_f32 v53, v54, v55
	ds_write_b128 v5, v[50:53] offset:816
	v_cvt_pk_bf16_f32 v50, v86, v87
	v_cvt_pk_bf16_f32 v51, v98, v99
	v_cvt_pk_bf16_f32 v52, v118, v119
	v_cvt_pk_bf16_f32 v53, v128, v129
	ds_write_b128 v5, v[50:53] offset:1088
	v_cvt_pk_bf16_f32 v50, v84, v85
; #define LAS __attribute__((address_space(3)))
; __device__ __forceinline__ unsigned pk2(float lo, float hi) { f32x2 v = {lo, hi}; bf16x2_t b = __builtin_convertvector(v, bf16x2_t); return __builtin_bit_cast(unsigned, b); }
; __device__ __forceinline__ void gmlp_unit(const GmlpP& P, int b, int ch, LAS unsigned char* lds, int wave, int lane_in) {
;     ...
;             for (int i = 0; i < 8; ++i) {
;                 const u32x4 raw = rawv[8 * hf + i];
;                 float v[8];
; #pragma unroll
;                 for (int j = 0; j < 4; ++j) { v[2 * j] = __builtin_bit_cast(float, raw[j] << 16); v[2 * j + 1] = __builtin_bit_cast(float, raw[j] & 0xffff0000u); }
;                 float sm = 0.f;
; #pragma unroll
;                 for (int j = 0; j < 8; ++j) sm += v[j];
;                 sm = row16_sum(sm);
;                 const float mu = sm * (1.0f / 128.0f);
;                 float sq = 0.f;
; #pragma unroll
;                 for (int j = 0; j < 8; ++j) { v[j] -= mu; sq += v[j] * v[j]; }
;                 sq = row16_sum(sq);
;                 const float rs = __builtin_amdgcn_rsqf(sq * (1.0f / 128.0f) + EPS);
; #pragma unroll
;                 for (int j = 0; j < 8; ++j) yv[j][i] = v[j] * rs * (j < 4 ? ga0[j & 3] : ga1[j & 3]) + (j < 4 ? be0[j & 3] : be1[j & 3]);
;             }
;             const int s0 = 64 * th + 16 * rr + 8 * hf;
;             LAS unsigned char* dst = lds + (gI * 128 + 8 * sub) * LDS_TT_PITCH + 16 * ((s0 >> 3) ^ sub);
; #pragma unroll
;             for (int j = 0; j < 8; ++j) {
;                 u32x4 w; w.x = pk2(yv[j][0], yv[j][1]); w.y = pk2(yv[j][2], yv[j][3]); w.z = pk2(yv[j][4], yv[j][5]); w.w = pk2(yv[j][6], yv[j][7]);
;                 *(LAS u32x4*)(dst + j * LDS_TT_PITCH) = w;
;             }
	v_cvt_pk_bf16_f32 v51, v96, v97
	v_cvt_pk_bf16_f32 v52, v60, v61
	v_cvt_pk_bf16_f32 v53, v130, v131
	ds_write_b128 v5, v[50:53] offset:1360
	v_cvt_pk_bf16_f32 v50, v82, v83
	v_cvt_pk_bf16_f32 v51, v72, v73
	v_cvt_pk_bf16_f32 v52, v120, v121
	v_cvt_pk_bf16_f32 v53, v132, v133
	v_lshlrev_b32_e32 v61, 16, v46
	v_lshlrev_b32_e32 v60, 16, v42
	ds_write_b128 v5, v[50:53] offset:1632
	v_cvt_pk_bf16_f32 v51, v62, v63
	v_cvt_pk_bf16_f32 v52, v64, v65
	v_and_b32_e32 v54, 0xffff0000, v45
	v_lshlrev_b32_e32 v59, 16, v49
	v_lshlrev_b32_e32 v58, 16, v45
	v_and_b32_e32 v55, 0xffff0000, v49
	v_and_b32_e32 v63, 0xffff0000, v46
	v_and_b32_e32 v62, 0xffff0000, v42
	v_lshlrev_b32_e32 v64, 16, v43
	v_and_b32_e32 v46, 0xffff0000, v43
	v_lshlrev_b32_e32 v43, 16, v48
	v_and_b32_e32 v45, 0xffff0000, v48
	v_pk_add_f32 v[48:49], v[60:61], 0 op_sel_hi:[1,0]
	v_lshlrev_b32_e32 v65, 16, v47
	v_pk_add_f32 v[48:49], v[48:49], v[62:63]
	v_and_b32_e32 v47, 0xffff0000, v47
	v_pk_add_f32 v[48:49], v[48:49], v[64:65]
	v_lshlrev_b32_e32 v42, 16, v44
	v_pk_add_f32 v[48:49], v[48:49], v[46:47]
	v_and_b32_e32 v44, 0xffff0000, v44
	v_pk_add_f32 v[48:49], v[48:49], v[42:43]
	v_cvt_pk_bf16_f32 v50, v70, v71
	v_pk_add_f32 v[48:49], v[48:49], v[44:45]
	v_mov_b32_e32 v72, v44
	v_pk_add_f32 v[48:49], v[48:49], v[58:59]
	v_mov_b32_e32 v73, v42
	v_pk_add_f32 v[48:49], v[48:49], v[54:55]
	v_mov_b32_e32 v84, v54
	v_mov_b32_e32 v85, v58
	v_mov_b32_dpp v70, v48 row_ror:8 row_mask:0xf bank_mask:0xf bound_ctrl:1
	v_mov_b32_dpp v71, v49 row_ror:8 row_mask:0xf bank_mask:0xf bound_ctrl:1
	v_pk_add_f32 v[48:49], v[48:49], v[70:71]
	v_mov_b32_e32 v42, v45
	v_mov_b32_e32 v58, v55
	v_mov_b32_dpp v70, v48 row_ror:4 row_mask:0xf bank_mask:0xf bound_ctrl:1
	v_mov_b32_dpp v71, v49 row_ror:4 row_mask:0xf bank_mask:0xf bound_ctrl:1
	v_pk_add_f32 v[48:49], v[48:49], v[70:71]
	v_cvt_pk_bf16_f32 v53, v56, v57
	ds_write_b128 v5, v[50:53] offset:1904
	v_mov_b32_dpp v70, v48 quad_perm:[2,3,0,1] row_mask:0xf bank_mask:0xf bound_ctrl:1
	v_mov_b32_dpp v71, v49 quad_perm:[2,3,0,1] row_mask:0xf bank_mask:0xf bound_ctrl:1
	v_pk_add_f32 v[48:49], v[48:49], v[70:71]
	v_and_b32_e32 v56, 0xffff0000, v37
	v_and_b32_e32 v57, 0xffff0000, v41
	v_mov_b32_dpp v70, v48 quad_perm:[1,0,3,2] row_mask:0xf bank_mask:0xf bound_ctrl:1
	v_mov_b32_dpp v71, v49 quad_perm:[1,0,3,2] row_mask:0xf bank_mask:0xf bound_ctrl:1
	v_pk_add_f32 v[48:49], v[48:49], v[70:71]
	v_mov_b32_e32 v90, v56
	v_pk_mul_f32 v[70:71], v[48:49], s[24:25] op_sel_hi:[1,0]
	v_pk_fma_f32 v[62:63], v[48:49], s[24:25], v[62:63] op_sel_hi:[1,0,1] neg_lo:[1,0,0] neg_hi:[1,0,0]
	v_pk_fma_f32 v[60:61], v[48:49], s[24:25], v[60:61] op_sel_hi:[1,0,1] neg_lo:[1,0,0] neg_hi:[1,0,0]
	v_pk_add_f32 v[72:73], v[72:73], v[70:71] op_sel_hi:[1,0] neg_lo:[0,1] neg_hi:[0,1]
	v_pk_add_f32 v[84:85], v[84:85], v[70:71] op_sel_hi:[1,0] neg_lo:[0,1] neg_hi:[0,1]
	v_pk_add_f32 v[42:43], v[42:43], v[70:71] op_sel:[0,1] neg_lo:[0,1] neg_hi:[0,1]
	v_pk_add_f32 v[58:59], v[58:59], v[70:71] op_sel:[0,1] neg_lo:[0,1] neg_hi:[0,1]
	v_pk_mul_f32 v[70:71], v[62:63], v[62:63]
	v_pk_fma_f32 v[64:65], v[48:49], s[24:25], v[64:65] op_sel_hi:[1,0,1] neg_lo:[1,0,0] neg_hi:[1,0,0]
	v_pk_fma_f32 v[70:71], v[60:61], v[60:61], v[70:71]
	v_pk_fma_f32 v[46:47], v[48:49], s[24:25], v[46:47] op_sel_hi:[1,0,1] neg_lo:[1,0,0] neg_hi:[1,0,0]
	v_pk_fma_f32 v[70:71], v[64:65], v[64:65], v[70:71]
	v_pk_mul_f32 v[82:83], v[72:73], v[72:73]
	v_pk_fma_f32 v[48:49], v[46:47], v[46:47], v[70:71]
	v_pk_mul_f32 v[86:87], v[84:85], v[84:85]
	v_add_f32_e32 v7, v83, v48
	v_add_f32_e32 v7, v82, v7
	v_add_f32_e32 v7, v87, v7
	v_add_f32_e32 v7, v86, v7
	v_pk_mul_f32 v[44:45], v[42:43], v[42:43]
	v_pk_mul_f32 v[54:55], v[58:59], v[58:59]
	v_add_f32_dpp v7, v7, v7 row_ror:8 row_mask:0xf bank_mask:0xf bound_ctrl:1
	s_nop 1
	v_add_f32_dpp v7, v7, v7 row_ror:4 row_mask:0xf bank_mask:0xf bound_ctrl:1
	s_nop 1
	v_add_f32_dpp v7, v7, v7 quad_perm:[2,3,0,1] row_mask:0xf bank_mask:0xf bound_ctrl:1
	s_nop 1
	v_add_f32_dpp v7, v7, v7 quad_perm:[1,0,3,2] row_mask:0xf bank_mask:0xf bound_ctrl:1
	v_fmamk_f32 v7, v7, 0x3c000000, v1
	v_rsq_f32_e32 v70, v7
	v_add_f32_e32 v7, v45, v49
	v_add_f32_e32 v7, v44, v7
	v_add_f32_e32 v7, v55, v7
	v_add_f32_e32 v7, v54, v7
	s_nop 1
	v_add_f32_dpp v7, v7, v7 row_ror:8 row_mask:0xf bank_mask:0xf bound_ctrl:1
	s_nop 1
	v_add_f32_dpp v7, v7, v7 row_ror:4 row_mask:0xf bank_mask:0xf bound_ctrl:1
	s_nop 1
	v_add_f32_dpp v7, v7, v7 quad_perm:[2,3,0,1] row_mask:0xf bank_mask:0xf bound_ctrl:1
	s_nop 1
	v_add_f32_dpp v7, v7, v7 quad_perm:[1,0,3,2] row_mask:0xf bank_mask:0xf bound_ctrl:1
	v_fmamk_f32 v7, v7, 0x3c000000, v1
	v_rsq_f32_e32 v71, v7
	s_nop 0
	v_pk_mul_f32 v[44:45], v[60:61], v[70:71]
	s_nop 0
	v_pk_fma_f32 v[54:55], v[10:11], v[44:45], v[14:15] op_sel_hi:[0,1,0]
	v_pk_mul_f32 v[44:45], v[62:63], v[70:71]
	v_lshlrev_b32_e32 v63, 16, v38
	v_pk_fma_f32 v[52:53], v[10:11], v[44:45], v[14:15] op_sel:[1,0,1]
	v_pk_mul_f32 v[44:45], v[64:65], v[70:71]
	v_lshlrev_b32_e32 v62, 16, v34
	v_pk_fma_f32 v[50:51], v[12:13], v[44:45], v[16:17] op_sel_hi:[0,1,0]
	v_pk_mul_f32 v[44:45], v[46:47], v[70:71]
	v_lshlrev_b32_e32 v61, 16, v41
	v_pk_fma_f32 v[48:49], v[74:75], v[44:45], v[76:77] op_sel_hi:[0,1,0]
	v_mov_b32_e32 v44, v73
	v_mov_b32_e32 v73, v42
	v_mov_b32_e32 v45, v43
	v_pk_mul_f32 v[42:43], v[72:73], v[70:71]
	v_lshlrev_b32_e32 v60, 16, v37
	v_and_b32_e32 v65, 0xffff0000, v38
	v_and_b32_e32 v64, 0xffff0000, v34
	v_lshlrev_b32_e32 v72, 16, v35
	v_and_b32_e32 v38, 0xffff0000, v35
	v_lshlrev_b32_e32 v35, 16, v40
	v_and_b32_e32 v37, 0xffff0000, v40
	v_pk_add_f32 v[40:41], v[62:63], 0 op_sel_hi:[1,0]
	v_lshlrev_b32_e32 v73, 16, v39
; __device__ __forceinline__ void gmlp_unit(const GmlpP& P, int b, int ch, LAS unsigned char* lds, int wave, int lane_in) {
;     ...
;             for (int i = 0; i < 8; ++i) {
;                 const u32x4 raw = rawv[8 * hf + i];
;                 float v[8];
; #pragma unroll
;                 for (int j = 0; j < 4; ++j) { v[2 * j] = __builtin_bit_cast(float, raw[j] << 16); v[2 * j + 1] = __builtin_bit_cast(float, raw[j] & 0xffff0000u); }
;                 float sm = 0.f;
; #pragma unroll
;                 for (int j = 0; j < 8; ++j) sm += v[j];
;                 sm = row16_sum(sm);
;                 const float mu = sm * (1.0f / 128.0f);
;                 float sq = 0.f;
; #pragma unroll
;                 for (int j = 0; j < 8; ++j) { v[j] -= mu; sq += v[j] * v[j]; }
;                 sq = row16_sum(sq);
;                 const float rs = __builtin_amdgcn_rsqf(sq * (1.0f / 128.0f) + EPS);
; #pragma unroll
;                 for (int j = 0; j < 8; ++j) yv[j][i] = v[j] * rs * (j < 4 ? ga0[j & 3] : ga1[j & 3]) + (j < 4 ? be0[j & 3] : be1[j & 3]);
	v_pk_add_f32 v[40:41], v[40:41], v[64:65]
	v_and_b32_e32 v39, 0xffff0000, v39
	v_pk_add_f32 v[40:41], v[40:41], v[72:73]
	v_lshlrev_b32_e32 v34, 16, v36
	v_pk_add_f32 v[40:41], v[40:41], v[38:39]
	v_and_b32_e32 v36, 0xffff0000, v36
	v_pk_add_f32 v[40:41], v[40:41], v[34:35]
	v_mov_b32_e32 v86, v36
	v_pk_add_f32 v[40:41], v[40:41], v[36:37]
	v_mov_b32_e32 v87, v34
	v_pk_add_f32 v[40:41], v[40:41], v[60:61]
	v_mov_b32_e32 v91, v60
	v_pk_add_f32 v[40:41], v[40:41], v[56:57]
	v_mov_b32_e32 v34, v37
	v_mov_b32_e32 v60, v57
	v_mov_b32_dpp v82, v40 row_ror:8 row_mask:0xf bank_mask:0xf bound_ctrl:1
	v_mov_b32_dpp v83, v41 row_ror:8 row_mask:0xf bank_mask:0xf bound_ctrl:1
	v_pk_add_f32 v[40:41], v[40:41], v[82:83]
	v_pk_mul_f32 v[44:45], v[44:45], v[70:71]
	s_nop 0
	v_mov_b32_dpp v82, v40 row_ror:4 row_mask:0xf bank_mask:0xf bound_ctrl:1
	v_mov_b32_dpp v83, v41 row_ror:4 row_mask:0xf bank_mask:0xf bound_ctrl:1
	v_pk_add_f32 v[40:41], v[40:41], v[82:83]
	v_pk_fma_f32 v[46:47], v[2:3], v[44:45], v[6:7] op_sel_hi:[0,1,0]
	v_pk_fma_f32 v[44:45], v[78:79], v[42:43], v[80:81] op_sel_hi:[0,1,0]
	v_mov_b32_dpp v82, v40 quad_perm:[2,3,0,1] row_mask:0xf bank_mask:0xf bound_ctrl:1
	v_mov_b32_dpp v83, v41 quad_perm:[2,3,0,1] row_mask:0xf bank_mask:0xf bound_ctrl:1
	v_pk_add_f32 v[40:41], v[40:41], v[82:83]
	v_mov_b32_e32 v42, v85
	v_mov_b32_e32 v43, v59
	v_mov_b32_dpp v82, v40 quad_perm:[1,0,3,2] row_mask:0xf bank_mask:0xf bound_ctrl:1
	v_mov_b32_dpp v83, v41 quad_perm:[1,0,3,2] row_mask:0xf bank_mask:0xf bound_ctrl:1
	v_pk_add_f32 v[40:41], v[40:41], v[82:83]
	v_pk_mul_f32 v[42:43], v[42:43], v[70:71]
	v_pk_mul_f32 v[82:83], v[40:41], s[24:25] op_sel_hi:[1,0]
	v_pk_fma_f32 v[62:63], v[40:41], s[24:25], v[62:63] op_sel_hi:[1,0,1] neg_lo:[1,0,0] neg_hi:[1,0,0]
	v_pk_add_f32 v[86:87], v[86:87], v[82:83] op_sel_hi:[1,0] neg_lo:[0,1] neg_hi:[0,1]
	v_pk_add_f32 v[90:91], v[90:91], v[82:83] op_sel_hi:[1,0] neg_lo:[0,1] neg_hi:[0,1]
	v_pk_add_f32 v[36:37], v[34:35], v[82:83] op_sel:[0,1] neg_lo:[0,1] neg_hi:[0,1]
	v_pk_add_f32 v[82:83], v[60:61], v[82:83] op_sel:[0,1] neg_lo:[0,1] neg_hi:[0,1]
	v_pk_fma_f32 v[60:61], v[40:41], s[24:25], v[64:65] op_sel_hi:[1,0,1] neg_lo:[1,0,0] neg_hi:[1,0,0]
	v_pk_fma_f32 v[72:73], v[40:41], s[24:25], v[72:73] op_sel_hi:[1,0,1] neg_lo:[1,0,0] neg_hi:[1,0,0]
	v_pk_mul_f32 v[64:65], v[60:61], v[60:61]
	v_pk_fma_f32 v[38:39], v[40:41], s[24:25], v[38:39] op_sel_hi:[1,0,1] neg_lo:[1,0,0] neg_hi:[1,0,0]
	v_pk_fma_f32 v[64:65], v[62:63], v[62:63], v[64:65]
	v_pk_mul_f32 v[88:89], v[86:87], v[86:87]
	v_pk_fma_f32 v[64:65], v[72:73], v[72:73], v[64:65]
	v_pk_fma_f32 v[42:43], v[4:5], v[42:43], v[8:9] op_sel_hi:[0,1,0]
	v_pk_fma_f32 v[40:41], v[38:39], v[38:39], v[64:65]
	v_pk_mul_f32 v[92:93], v[90:91], v[90:91]
	v_add_f32_e32 v5, v89, v40
	v_add_f32_e32 v5, v88, v5
	v_add_f32_e32 v5, v93, v5
	v_add_f32_e32 v5, v92, v5
	v_pk_mul_f32 v[34:35], v[36:37], v[36:37]
	v_pk_mul_f32 v[56:57], v[82:83], v[82:83]
	v_add_f32_dpp v5, v5, v5 row_ror:8 row_mask:0xf bank_mask:0xf bound_ctrl:1
	v_mov_b32_e32 v85, v58
	v_lshlrev_b32_e32 v88, 16, v27
	v_add_f32_dpp v5, v5, v5 row_ror:4 row_mask:0xf bank_mask:0xf bound_ctrl:1
	v_lshlrev_b32_e32 v89, 16, v31
	v_and_b32_e32 v31, 0xffff0000, v31
	v_add_f32_dpp v5, v5, v5 quad_perm:[2,3,0,1] row_mask:0xf bank_mask:0xf bound_ctrl:1
	s_nop 1
	v_add_f32_dpp v5, v5, v5 quad_perm:[1,0,3,2] row_mask:0xf bank_mask:0xf bound_ctrl:1
	v_fmamk_f32 v5, v5, 0x3c000000, v1
	v_rsq_f32_e32 v64, v5
	v_add_f32_e32 v5, v35, v41
	v_add_f32_e32 v5, v34, v5
	v_add_f32_e32 v5, v57, v5
	v_add_f32_e32 v5, v56, v5
	v_pk_mul_f32 v[34:35], v[84:85], v[70:71]
	v_lshlrev_b32_e32 v85, 16, v30
	v_add_f32_dpp v5, v5, v5 row_ror:8 row_mask:0xf bank_mask:0xf bound_ctrl:1
	v_lshlrev_b32_e32 v84, 16, v26
	v_and_b32_e32 v70, 0xffff0000, v29
	v_add_f32_dpp v5, v5, v5 row_ror:4 row_mask:0xf bank_mask:0xf bound_ctrl:1
	v_and_b32_e32 v71, 0xffff0000, v33
	v_mov_b32_e32 v98, v70
	v_add_f32_dpp v5, v5, v5 quad_perm:[2,3,0,1] row_mask:0xf bank_mask:0xf bound_ctrl:1
	v_pk_fma_f32 v[34:35], v[66:67], v[34:35], v[68:69] op_sel_hi:[0,1,0]
	s_nop 0
	v_add_f32_dpp v5, v5, v5 quad_perm:[1,0,3,2] row_mask:0xf bank_mask:0xf bound_ctrl:1
	v_fmamk_f32 v5, v5, 0x3c000000, v1
	v_rsq_f32_e32 v65, v5
	s_nop 0
	v_pk_mul_f32 v[40:41], v[62:63], v[64:65]
	v_pk_mul_f32 v[38:39], v[38:39], v[64:65]
	v_pk_fma_f32 v[62:63], v[10:11], v[40:41], v[14:15] op_sel_hi:[0,1,0]
	v_pk_mul_f32 v[40:41], v[60:61], v[64:65]
	v_pk_fma_f32 v[56:57], v[74:75], v[38:39], v[76:77] op_sel_hi:[0,1,0]
	v_mov_b32_e32 v38, v87
	v_mov_b32_e32 v87, v36
	v_pk_fma_f32 v[60:61], v[10:11], v[40:41], v[14:15] op_sel:[1,0,1]
	v_pk_mul_f32 v[40:41], v[72:73], v[64:65]
	v_mov_b32_e32 v39, v37
	v_pk_mul_f32 v[36:37], v[86:87], v[64:65]
	v_lshlrev_b32_e32 v73, 16, v33
	v_lshlrev_b32_e32 v72, 16, v29
	v_and_b32_e32 v87, 0xffff0000, v30
	v_and_b32_e32 v86, 0xffff0000, v26
	v_and_b32_e32 v30, 0xffff0000, v27
	v_lshlrev_b32_e32 v27, 16, v32
	v_and_b32_e32 v29, 0xffff0000, v32
	v_pk_add_f32 v[32:33], v[84:85], 0 op_sel_hi:[1,0]
	v_lshlrev_b32_e32 v26, 16, v28
	v_pk_add_f32 v[32:33], v[32:33], v[86:87]
	v_and_b32_e32 v28, 0xffff0000, v28
	v_pk_add_f32 v[32:33], v[32:33], v[88:89]
	v_mov_b32_e32 v94, v28
	v_pk_add_f32 v[32:33], v[32:33], v[30:31]
	v_mov_b32_e32 v95, v26
	v_pk_add_f32 v[32:33], v[32:33], v[26:27]
	v_mov_b32_e32 v99, v72
	v_pk_add_f32 v[32:33], v[32:33], v[28:29]
	v_mov_b32_e32 v26, v29
	v_pk_add_f32 v[32:33], v[32:33], v[72:73]
	v_mov_b32_e32 v72, v71
	v_pk_add_f32 v[32:33], v[32:33], v[70:71]
	v_pk_mul_f32 v[38:39], v[38:39], v[64:65]
	v_pk_fma_f32 v[58:59], v[12:13], v[40:41], v[16:17] op_sel_hi:[0,1,0]
; __device__ __forceinline__ void gmlp_unit(const GmlpP& P, int b, int ch, LAS unsigned char* lds, int wave, int lane_in) {
;     ...
;             for (int i = 0; i < 8; ++i) {
;                 const u32x4 raw = rawv[8 * hf + i];
;                 float v[8];
; #pragma unroll
;                 for (int j = 0; j < 4; ++j) { v[2 * j] = __builtin_bit_cast(float, raw[j] << 16); v[2 * j + 1] = __builtin_bit_cast(float, raw[j] & 0xffff0000u); }
;                 float sm = 0.f;
; #pragma unroll
;                 for (int j = 0; j < 8; ++j) sm += v[j];
;                 sm = row16_sum(sm);
;                 const float mu = sm * (1.0f / 128.0f);
;                 float sq = 0.f;
; #pragma unroll
;                 for (int j = 0; j < 8; ++j) { v[j] -= mu; sq += v[j] * v[j]; }
;                 sq = row16_sum(sq);
;                 const float rs = __builtin_amdgcn_rsqf(sq * (1.0f / 128.0f) + EPS);
; #pragma unroll
;                 for (int j = 0; j < 8; ++j) yv[j][i] = v[j] * rs * (j < 4 ? ga0[j & 3] : ga1[j & 3]) + (j < 4 ? be0[j & 3] : be1[j & 3]);
	v_mov_b32_dpp v92, v32 row_ror:8 row_mask:0xf bank_mask:0xf bound_ctrl:1
	v_mov_b32_dpp v93, v33 row_ror:8 row_mask:0xf bank_mask:0xf bound_ctrl:1
	v_pk_add_f32 v[32:33], v[32:33], v[92:93]
	v_pk_fma_f32 v[40:41], v[2:3], v[38:39], v[6:7] op_sel_hi:[0,1,0]
	v_pk_fma_f32 v[38:39], v[78:79], v[36:37], v[80:81] op_sel_hi:[0,1,0]
	v_mov_b32_dpp v92, v32 row_ror:4 row_mask:0xf bank_mask:0xf bound_ctrl:1
	v_mov_b32_dpp v93, v33 row_ror:4 row_mask:0xf bank_mask:0xf bound_ctrl:1
	v_pk_add_f32 v[32:33], v[32:33], v[92:93]
	v_mov_b32_e32 v36, v91
	v_mov_b32_e32 v37, v83
	v_mov_b32_dpp v92, v32 quad_perm:[2,3,0,1] row_mask:0xf bank_mask:0xf bound_ctrl:1
	v_mov_b32_dpp v93, v33 quad_perm:[2,3,0,1] row_mask:0xf bank_mask:0xf bound_ctrl:1
	v_pk_add_f32 v[32:33], v[32:33], v[92:93]
	v_pk_mul_f32 v[36:37], v[36:37], v[64:65]
	v_mov_b32_e32 v91, v82
	v_mov_b32_dpp v92, v32 quad_perm:[1,0,3,2] row_mask:0xf bank_mask:0xf bound_ctrl:1
	v_mov_b32_dpp v93, v33 quad_perm:[1,0,3,2] row_mask:0xf bank_mask:0xf bound_ctrl:1
	v_pk_add_f32 v[32:33], v[32:33], v[92:93]
	v_pk_fma_f32 v[36:37], v[4:5], v[36:37], v[8:9] op_sel_hi:[0,1,0]
	v_pk_mul_f32 v[92:93], v[32:33], s[24:25] op_sel_hi:[1,0]
	v_pk_fma_f32 v[86:87], v[32:33], s[24:25], v[86:87] op_sel_hi:[1,0,1] neg_lo:[1,0,0] neg_hi:[1,0,0]
	v_pk_fma_f32 v[84:85], v[32:33], s[24:25], v[84:85] op_sel_hi:[1,0,1] neg_lo:[1,0,0] neg_hi:[1,0,0]
	v_pk_add_f32 v[94:95], v[94:95], v[92:93] op_sel_hi:[1,0] neg_lo:[0,1] neg_hi:[0,1]
	v_pk_add_f32 v[98:99], v[98:99], v[92:93] op_sel_hi:[1,0] neg_lo:[0,1] neg_hi:[0,1]
	v_pk_add_f32 v[26:27], v[26:27], v[92:93] op_sel:[0,1] neg_lo:[0,1] neg_hi:[0,1]
	v_pk_add_f32 v[70:71], v[72:73], v[92:93] op_sel:[0,1] neg_lo:[0,1] neg_hi:[0,1]
	v_pk_mul_f32 v[92:93], v[86:87], v[86:87]
	v_pk_fma_f32 v[88:89], v[32:33], s[24:25], v[88:89] op_sel_hi:[1,0,1] neg_lo:[1,0,0] neg_hi:[1,0,0]
	v_pk_fma_f32 v[92:93], v[84:85], v[84:85], v[92:93]
	v_pk_fma_f32 v[30:31], v[32:33], s[24:25], v[30:31] op_sel_hi:[1,0,1] neg_lo:[1,0,0] neg_hi:[1,0,0]
	v_pk_fma_f32 v[92:93], v[88:89], v[88:89], v[92:93]
	v_pk_mul_f32 v[96:97], v[94:95], v[94:95]
	v_pk_fma_f32 v[32:33], v[30:31], v[30:31], v[92:93]
	v_pk_mul_f32 v[100:101], v[98:99], v[98:99]
	v_add_f32_e32 v5, v97, v32
	v_add_f32_e32 v5, v96, v5
	v_add_f32_e32 v5, v101, v5
	v_add_f32_e32 v5, v100, v5
	v_pk_mul_f32 v[28:29], v[26:27], v[26:27]
	v_pk_mul_f32 v[72:73], v[70:71], v[70:71]
	v_add_f32_dpp v5, v5, v5 row_ror:8 row_mask:0xf bank_mask:0xf bound_ctrl:1
	v_lshlrev_b32_e32 v93, 16, v22
	v_lshlrev_b32_e32 v92, 16, v18
	v_add_f32_dpp v5, v5, v5 row_ror:4 row_mask:0xf bank_mask:0xf bound_ctrl:1
	v_lshlrev_b32_e32 v96, 16, v19
	v_lshlrev_b32_e32 v97, 16, v23
	v_add_f32_dpp v5, v5, v5 quad_perm:[2,3,0,1] row_mask:0xf bank_mask:0xf bound_ctrl:1
	v_and_b32_e32 v23, 0xffff0000, v23
	s_nop 0
	v_add_f32_dpp v5, v5, v5 quad_perm:[1,0,3,2] row_mask:0xf bank_mask:0xf bound_ctrl:1
	v_fmamk_f32 v5, v5, 0x3c000000, v1
	v_rsq_f32_e32 v32, v5
	v_add_f32_e32 v5, v29, v33
	v_add_f32_e32 v5, v28, v5
	v_add_f32_e32 v5, v73, v5
	v_add_f32_e32 v5, v72, v5
	v_pk_mul_f32 v[28:29], v[90:91], v[64:65]
	v_lshlrev_b32_e32 v91, 16, v25
	v_add_f32_dpp v5, v5, v5 row_ror:8 row_mask:0xf bank_mask:0xf bound_ctrl:1
	v_lshlrev_b32_e32 v90, 16, v21
	v_mov_b32_e32 v107, v90
	v_add_f32_dpp v5, v5, v5 row_ror:4 row_mask:0xf bank_mask:0xf bound_ctrl:1
	v_pk_fma_f32 v[28:29], v[66:67], v[28:29], v[68:69] op_sel_hi:[0,1,0]
	s_nop 0
	v_add_f32_dpp v5, v5, v5 quad_perm:[2,3,0,1] row_mask:0xf bank_mask:0xf bound_ctrl:1
	s_nop 1
	v_add_f32_dpp v5, v5, v5 quad_perm:[1,0,3,2] row_mask:0xf bank_mask:0xf bound_ctrl:1
	v_fmamk_f32 v5, v5, 0x3c000000, v1
	v_rsq_f32_e32 v33, v5
	s_nop 0
	v_pk_mul_f32 v[64:65], v[84:85], v[32:33]
	v_mov_b32_e32 v84, v95
	v_mov_b32_e32 v95, v26
	v_pk_mul_f32 v[82:83], v[88:89], v[32:33]
	v_mov_b32_e32 v85, v27
	v_pk_mul_f32 v[26:27], v[94:95], v[32:33]
	v_and_b32_e32 v88, 0xffff0000, v21
	v_and_b32_e32 v89, 0xffff0000, v25
	v_and_b32_e32 v95, 0xffff0000, v22
	v_and_b32_e32 v94, 0xffff0000, v18
	v_and_b32_e32 v22, 0xffff0000, v19
	v_lshlrev_b32_e32 v19, 16, v24
	v_and_b32_e32 v21, 0xffff0000, v24
	v_pk_add_f32 v[24:25], v[92:93], 0 op_sel_hi:[1,0]
	v_lshlrev_b32_e32 v18, 16, v20
	v_pk_add_f32 v[24:25], v[24:25], v[94:95]
	v_and_b32_e32 v20, 0xffff0000, v20
	v_pk_add_f32 v[24:25], v[24:25], v[96:97]
	v_mov_b32_e32 v102, v20
	v_pk_add_f32 v[24:25], v[24:25], v[22:23]
	v_mov_b32_e32 v103, v18
	v_pk_add_f32 v[24:25], v[24:25], v[18:19]
	v_mov_b32_e32 v106, v88
	v_pk_add_f32 v[24:25], v[24:25], v[20:21]
	v_mov_b32_e32 v18, v21
	v_pk_add_f32 v[24:25], v[24:25], v[90:91]
	v_mov_b32_e32 v90, v89
	v_pk_add_f32 v[24:25], v[24:25], v[88:89]
	v_pk_mul_f32 v[72:73], v[86:87], v[32:33]
	v_mov_b32_e32 v86, v99
	v_mov_b32_dpp v100, v24 row_ror:8 row_mask:0xf bank_mask:0xf bound_ctrl:1
	v_mov_b32_dpp v101, v25 row_ror:8 row_mask:0xf bank_mask:0xf bound_ctrl:1
	v_pk_add_f32 v[24:25], v[24:25], v[100:101]
	v_mov_b32_e32 v87, v71
	v_pk_mul_f32 v[86:87], v[86:87], v[32:33]
	v_mov_b32_dpp v100, v24 row_ror:4 row_mask:0xf bank_mask:0xf bound_ctrl:1
	v_mov_b32_dpp v101, v25 row_ror:4 row_mask:0xf bank_mask:0xf bound_ctrl:1
	v_pk_add_f32 v[24:25], v[24:25], v[100:101]
	v_pk_fma_f32 v[86:87], v[4:5], v[86:87], v[8:9] op_sel_hi:[0,1,0]
	v_mov_b32_e32 v99, v70
	v_mov_b32_dpp v100, v24 quad_perm:[2,3,0,1] row_mask:0xf bank_mask:0xf bound_ctrl:1
	v_mov_b32_dpp v101, v25 quad_perm:[2,3,0,1] row_mask:0xf bank_mask:0xf bound_ctrl:1
	v_pk_add_f32 v[24:25], v[24:25], v[100:101]
	v_pk_mul_f32 v[30:31], v[30:31], v[32:33]
	v_pk_mul_f32 v[84:85], v[84:85], v[32:33]
	v_mov_b32_dpp v100, v24 quad_perm:[1,0,3,2] row_mask:0xf bank_mask:0xf bound_ctrl:1
; #define LAS __attribute__((address_space(3)))
; __device__ __forceinline__ unsigned pk2(float lo, float hi) { f32x2 v = {lo, hi}; bf16x2_t b = __builtin_convertvector(v, bf16x2_t); return __builtin_bit_cast(unsigned, b); }
; __device__ __forceinline__ void gmlp_unit(const GmlpP& P, int b, int ch, LAS unsigned char* lds, int wave, int lane_in) {
;     ...
;                 sm = row16_sum(sm);
;                 const float mu = sm * (1.0f / 128.0f);
;                 float sq = 0.f;
; #pragma unroll
;                 for (int j = 0; j < 8; ++j) { v[j] -= mu; sq += v[j] * v[j]; }
;                 sq = row16_sum(sq);
;                 const float rs = __builtin_amdgcn_rsqf(sq * (1.0f / 128.0f) + EPS);
; #pragma unroll
;                 for (int j = 0; j < 8; ++j) yv[j][i] = v[j] * rs * (j < 4 ? ga0[j & 3] : ga1[j & 3]) + (j < 4 ? be0[j & 3] : be1[j & 3]);
;             }
;             const int s0 = 64 * th + 16 * rr + 8 * hf;
;             LAS unsigned char* dst = lds + (gI * 128 + 8 * sub) * LDS_TT_PITCH + 16 * ((s0 >> 3) ^ sub);
; #pragma unroll
;             for (int j = 0; j < 8; ++j) {
;                 u32x4 w; w.x = pk2(yv[j][0], yv[j][1]); w.y = pk2(yv[j][2], yv[j][3]); w.z = pk2(yv[j][4], yv[j][5]); w.w = pk2(yv[j][6], yv[j][7]);
;                 *(LAS u32x4*)(dst + j * LDS_TT_PITCH) = w;
;             }
;             asm volatile("" ::: "memory");
;         }
;     }
;     const int r32 = lane & 31, h = lane >> 5;
;     const int tt0 = th, tt1 = 3 - th;
;     bf16x8 bw0[4], bw1[8];
;     { const bf16_t* w0p = P.wsb + ((size_t)(gI * 128 + 32 * tt0 + r32) * 128 + 8 * h);
;       const bf16_t* w1p = P.wsb + ((size_t)(gI * 128 + 32 * tt1 + r32) * 128 + 8 * h);
; #pragma unroll
;       for (int ks = 0; ks < 4; ++ks) bw0[ks] = *(const bf16x8*)(w0p + 16 * ks);
; #pragma unroll
;       for (int ks = 0; ks < 8; ++ks) bw1[ks] = *(const bf16x8*)(w1p + 16 * ks); }
;     __syncthreads();
	v_mov_b32_dpp v101, v25 quad_perm:[1,0,3,2] row_mask:0xf bank_mask:0xf bound_ctrl:1
	v_pk_add_f32 v[24:25], v[24:25], v[100:101]
	v_pk_fma_f32 v[64:65], v[10:11], v[64:65], v[14:15] op_sel_hi:[0,1,0]
	v_pk_mul_f32 v[100:101], v[24:25], s[24:25] op_sel_hi:[1,0]
	v_pk_fma_f32 v[94:95], v[24:25], s[24:25], v[94:95] op_sel_hi:[1,0,1] neg_lo:[1,0,0] neg_hi:[1,0,0]
	v_pk_fma_f32 v[92:93], v[24:25], s[24:25], v[92:93] op_sel_hi:[1,0,1] neg_lo:[1,0,0] neg_hi:[1,0,0]
	v_pk_add_f32 v[102:103], v[102:103], v[100:101] op_sel_hi:[1,0] neg_lo:[0,1] neg_hi:[0,1]
	v_pk_add_f32 v[106:107], v[106:107], v[100:101] op_sel_hi:[1,0] neg_lo:[0,1] neg_hi:[0,1]
	v_pk_add_f32 v[18:19], v[18:19], v[100:101] op_sel:[0,1] neg_lo:[0,1] neg_hi:[0,1]
	v_pk_add_f32 v[88:89], v[90:91], v[100:101] op_sel:[0,1] neg_lo:[0,1] neg_hi:[0,1]
	v_pk_mul_f32 v[100:101], v[94:95], v[94:95]
	v_pk_fma_f32 v[96:97], v[24:25], s[24:25], v[96:97] op_sel_hi:[1,0,1] neg_lo:[1,0,0] neg_hi:[1,0,0]
	v_pk_fma_f32 v[100:101], v[92:93], v[92:93], v[100:101]
	v_pk_fma_f32 v[22:23], v[24:25], s[24:25], v[22:23] op_sel_hi:[1,0,1] neg_lo:[1,0,0] neg_hi:[1,0,0]
	v_pk_fma_f32 v[100:101], v[96:97], v[96:97], v[100:101]
	v_pk_mul_f32 v[104:105], v[102:103], v[102:103]
	v_pk_fma_f32 v[24:25], v[22:23], v[22:23], v[100:101]
	v_pk_mul_f32 v[110:111], v[106:107], v[106:107]
	v_add_f32_e32 v5, v105, v24
	v_add_f32_e32 v5, v104, v5
	v_add_f32_e32 v5, v111, v5
	v_add_f32_e32 v5, v110, v5
	v_pk_mul_f32 v[20:21], v[18:19], v[18:19]
	v_pk_mul_f32 v[90:91], v[88:89], v[88:89]
	v_add_f32_dpp v5, v5, v5 row_ror:8 row_mask:0xf bank_mask:0xf bound_ctrl:1
	v_pk_fma_f32 v[72:73], v[10:11], v[72:73], v[14:15] op_sel:[1,0,1]
	v_pk_fma_f32 v[82:83], v[12:13], v[82:83], v[16:17] op_sel_hi:[0,1,0]
	v_add_f32_dpp v5, v5, v5 row_ror:4 row_mask:0xf bank_mask:0xf bound_ctrl:1
	v_pk_fma_f32 v[84:85], v[2:3], v[84:85], v[6:7] op_sel_hi:[0,1,0]
	v_pk_fma_f32 v[30:31], v[74:75], v[30:31], v[76:77] op_sel_hi:[0,1,0]
	v_add_f32_dpp v5, v5, v5 quad_perm:[2,3,0,1] row_mask:0xf bank_mask:0xf bound_ctrl:1
	v_pk_fma_f32 v[26:27], v[78:79], v[26:27], v[80:81] op_sel_hi:[0,1,0]
	s_nop 0
	v_add_f32_dpp v5, v5, v5 quad_perm:[1,0,3,2] row_mask:0xf bank_mask:0xf bound_ctrl:1
	v_fmamk_f32 v5, v5, 0x3c000000, v1
	v_rsq_f32_e32 v24, v5
	v_add_f32_e32 v5, v21, v25
	v_add_f32_e32 v5, v20, v5
	v_add_f32_e32 v5, v91, v5
	v_add_f32_e32 v5, v90, v5
	v_pk_mul_f32 v[20:21], v[98:99], v[32:33]
	s_nop 0
	v_add_f32_dpp v5, v5, v5 row_ror:8 row_mask:0xf bank_mask:0xf bound_ctrl:1
	v_pk_fma_f32 v[20:21], v[66:67], v[20:21], v[68:69] op_sel_hi:[0,1,0]
	s_nop 0
	v_add_f32_dpp v5, v5, v5 row_ror:4 row_mask:0xf bank_mask:0xf bound_ctrl:1
	s_nop 1
	v_add_f32_dpp v5, v5, v5 quad_perm:[2,3,0,1] row_mask:0xf bank_mask:0xf bound_ctrl:1
	s_nop 1
	v_add_f32_dpp v5, v5, v5 quad_perm:[1,0,3,2] row_mask:0xf bank_mask:0xf bound_ctrl:1
	v_fmamk_f32 v5, v5, 0x3c000000, v1
	v_rsq_f32_e32 v25, v5
	s_nop 0
	v_pk_mul_f32 v[32:33], v[92:93], v[24:25]
	v_pk_mul_f32 v[70:71], v[94:95], v[24:25]
	v_pk_fma_f32 v[32:33], v[10:11], v[32:33], v[14:15] op_sel_hi:[0,1,0]
	v_pk_fma_f32 v[10:11], v[10:11], v[70:71], v[14:15] op_sel:[1,0,1]
	v_pk_mul_f32 v[14:15], v[96:97], v[24:25]
	s_nop 0
	v_pk_fma_f32 v[12:13], v[12:13], v[14:15], v[16:17] op_sel_hi:[0,1,0]
	v_mov_b32_e32 v16, v103
	v_mov_b32_e32 v17, v19
	v_mov_b32_e32 v103, v18
	v_mov_b32_e32 v18, v107
	v_mov_b32_e32 v19, v89
	v_pk_mul_f32 v[16:17], v[16:17], v[24:25]
	v_pk_mul_f32 v[18:19], v[18:19], v[24:25]
	v_mov_b32_e32 v107, v88
	v_pk_fma_f32 v[6:7], v[2:3], v[16:17], v[6:7] op_sel_hi:[0,1,0]
	v_pk_fma_f32 v[8:9], v[4:5], v[18:19], v[8:9] op_sel_hi:[0,1,0]
	v_pk_mul_f32 v[4:5], v[106:107], v[24:25]
	v_bitop3_b32 v2, v3, v108, 1 bitop3:0x36
	v_pk_mul_f32 v[14:15], v[22:23], v[24:25]
	v_pk_fma_f32 v[18:19], v[66:67], v[4:5], v[68:69] op_sel_hi:[0,1,0]
	v_lshl_add_u32 v22, v2, 4, v75
	v_cvt_pk_bf16_f32 v2, v54, v55
	v_cvt_pk_bf16_f32 v3, v62, v63
	v_cvt_pk_bf16_f32 v4, v64, v65
	v_cvt_pk_bf16_f32 v5, v32, v33
	ds_write_b128 v22, v[2:5]
	v_cvt_pk_bf16_f32 v2, v52, v53
	v_cvt_pk_bf16_f32 v3, v60, v61
	v_cvt_pk_bf16_f32 v4, v72, v73
	v_cvt_pk_bf16_f32 v5, v10, v11
	v_pk_fma_f32 v[14:15], v[74:75], v[14:15], v[76:77] op_sel_hi:[0,1,0]
	ds_write_b128 v22, v[2:5] offset:272
	v_cvt_pk_bf16_f32 v2, v50, v51
	v_cvt_pk_bf16_f32 v3, v58, v59
	v_cvt_pk_bf16_f32 v4, v82, v83
	v_cvt_pk_bf16_f32 v5, v12, v13
	v_pk_mul_f32 v[16:17], v[102:103], v[24:25]
	ds_write_b128 v22, v[2:5] offset:544
	v_cvt_pk_bf16_f32 v2, v48, v49
	v_cvt_pk_bf16_f32 v3, v56, v57
	v_cvt_pk_bf16_f32 v4, v30, v31
	v_cvt_pk_bf16_f32 v5, v14, v15
	v_pk_fma_f32 v[16:17], v[78:79], v[16:17], v[80:81] op_sel_hi:[0,1,0]
	ds_write_b128 v22, v[2:5] offset:816
	v_cvt_pk_bf16_f32 v2, v46, v47
	v_cvt_pk_bf16_f32 v3, v40, v41
	v_cvt_pk_bf16_f32 v4, v84, v85
	v_cvt_pk_bf16_f32 v5, v6, v7
	ds_write_b128 v22, v[2:5] offset:1088
	v_cvt_pk_bf16_f32 v2, v44, v45
	v_cvt_pk_bf16_f32 v3, v38, v39
	v_cvt_pk_bf16_f32 v4, v26, v27
	v_cvt_pk_bf16_f32 v5, v16, v17
	ds_write_b128 v22, v[2:5] offset:1360
	v_cvt_pk_bf16_f32 v2, v42, v43
	v_cvt_pk_bf16_f32 v3, v36, v37
	v_cvt_pk_bf16_f32 v4, v86, v87
	v_cvt_pk_bf16_f32 v5, v8, v9
	ds_write_b128 v22, v[2:5] offset:1632
	v_cvt_pk_bf16_f32 v2, v34, v35
	v_cvt_pk_bf16_f32 v3, v28, v29
	v_cvt_pk_bf16_f32 v4, v20, v21
	v_cvt_pk_bf16_f32 v5, v18, v19
	ds_write_b128 v22, v[2:5] offset:1904
	v_or_b32_e32 v2, s22, v154
	v_ashrrev_i32_e32 v3, 31, v2
	v_lshlrev_b32_e32 v4, 3, v140
	v_ashrrev_i32_e32 v5, 31, v4
	v_lshlrev_b64 v[2:3], 8, v[2:3]
	v_lshl_add_u64 v[2:3], s[0:1], 0, v[2:3]
	v_lshlrev_b64 v[6:7], 1, v[4:5]
	v_lshl_add_u64 v[10:11], v[2:3], 0, v[6:7]
	global_load_dwordx4 v[2:5], v[10:11], off
	v_or_b32_e32 v8, s25, v154
	v_ashrrev_i32_e32 v9, 31, v8
	v_lshlrev_b64 v[8:9], 8, v[8:9]
	v_lshl_add_u64 v[8:9], s[0:1], 0, v[8:9]
	v_lshl_add_u64 v[12:13], v[8:9], 0, v[6:7]
	global_load_dwordx4 v[6:9], v[12:13], off
	global_load_dwordx4 v[144:147], v[10:11], off offset:32
	global_load_dwordx4 v[148:151], v[10:11], off offset:64
	global_load_dwordx4 v[156:159], v[10:11], off offset:96
	global_load_dwordx4 v[160:163], v[12:13], off offset:32
	global_load_dwordx4 v[164:167], v[12:13], off offset:64
	global_load_dwordx4 v[168:171], v[12:13], off offset:96
	global_load_dwordx4 v[172:175], v[12:13], off offset:128
	global_load_dwordx4 v[176:179], v[12:13], off offset:160
	global_load_dwordx4 v[134:137], v[12:13], off offset:192
	global_load_dwordx4 v[130:133], v[12:13], off offset:224
	v_or_b32_e32 v14, 32, v154
	v_or_b32_e32 v10, s6, v154
	v_or_b32_e32 v15, s6, v14
	v_mul_lo_u32 v10, v10, s48
	v_mul_lo_u32 v15, v15, s48
	v_lshrrev_b32_e32 v190, 3, v14
	v_add_u32_e32 v155, 0, v10
	v_xor_b32_e32 v10, v188, v140
	v_add_u32_e32 v189, 0, v15
	v_xor_b32_e32 v14, v190, v140
	v_lshl_add_u32 v10, v10, 4, v155
	v_lshl_add_u32 v14, v14, 4, v189
	s_waitcnt lgkmcnt(0)
	s_barrier
; #define LAS __attribute__((address_space(3)))
; __device__ __forceinline__ void gmlp_unit(const GmlpP& P, int b, int ch, LAS unsigned char* lds, int wave, int lane_in) {
;     ...
;     {
; #pragma unroll
;         for (int ks = 0; ks < 8; ++ks)
; #pragma unroll
;             for (int mt = 0; mt < 4; ++mt) {
;                 const int cc = 32 * mt + r32;
;                 const bf16x8 a = *(const LAS bf16x8*)(lds + (gI * 128 + cc) * LDS_TT_PITCH + 16 * ((2 * ks + h) ^ ((cc >> 3) & 15)));
;                 if (ks < 4) acc[mt][0] = __builtin_amdgcn_mfma_f32_32x32x16_bf16(a, bw0[ks], acc[mt][0], 0, 0, 0);
;                 acc[mt][1] = __builtin_amdgcn_mfma_f32_32x32x16_bf16(a, bw1[ks], acc[mt][1], 0, 0, 0);
;                 if (mt == 3 && (ks & 1)) asm volatile("" ::: "memory");
;             }
;     }
	ds_read_b128 v[10:13], v10
	ds_read_b128 v[14:17], v14
	s_waitcnt vmcnt(11) lgkmcnt(1)
	v_mfma_f32_32x32x16_bf16 v[114:129], v[10:13], v[2:5], 0
	v_lshl_add_u32 v153, v153, 4, v155
	ds_read_b128 v[180:183], v153
	v_xor_b32_e32 v153, v190, v152
	v_lshl_add_u32 v153, v153, 4, v189
	ds_read_b128 v[184:187], v153
	s_waitcnt vmcnt(10)
	v_mfma_f32_32x32x16_bf16 v[50:65], v[10:13], v[6:9], 0
	v_or_b32_e32 v10, 64, v154
	v_or_b32_e32 v11, s6, v10
	v_mul_lo_u32 v11, v11, s48
	v_lshrrev_b32_e32 v192, 3, v10
	v_add_u32_e32 v191, 0, v11
	v_xor_b32_e32 v10, v192, v140
	v_lshl_add_u32 v10, v10, 4, v191
	s_waitcnt lgkmcnt(2)
	v_mfma_f32_32x32x16_bf16 v[98:113], v[14:17], v[2:5], 0
	ds_read_b128 v[10:13], v10
	v_xor_b32_e32 v153, v192, v152
	v_lshl_add_u32 v153, v153, 4, v191
	v_mfma_f32_32x32x16_bf16 v[34:49], v[14:17], v[6:9], 0
	v_or_b32_e32 v14, 0x60, v154
	v_or_b32_e32 v15, s6, v14
	v_mul_lo_u32 v15, v15, s48
	v_lshrrev_b32_e32 v194, 3, v14
	v_add_u32_e32 v193, 0, v15
	v_xor_b32_e32 v14, v194, v140
	v_lshl_add_u32 v14, v14, 4, v193
	ds_read_b128 v[14:17], v14
	v_xor_b32_e32 v152, v194, v152
	v_lshl_add_u32 v152, v152, 4, v193
	s_waitcnt vmcnt(9) lgkmcnt(3)
	v_mfma_f32_32x32x16_bf16 v[114:129], v[180:183], v[144:147], v[114:129]
	s_waitcnt vmcnt(6)
	v_mfma_f32_32x32x16_bf16 v[50:65], v[180:183], v[160:163], v[50:65]
	ds_read_b128 v[180:183], v153
	s_waitcnt lgkmcnt(3)
	v_mfma_f32_32x32x16_bf16 v[98:113], v[184:187], v[144:147], v[98:113]
	v_mfma_f32_32x32x16_bf16 v[34:49], v[184:187], v[160:163], v[34:49]
	ds_read_b128 v[184:187], v152
	v_add_u32_e32 v152, 4, v140
	v_xor_b32_e32 v153, v190, v152
	v_lshl_add_u32 v153, v153, 4, v189
	s_waitcnt lgkmcnt(3)
	v_mfma_f32_32x32x16_bf16 v[82:97], v[10:13], v[2:5], 0
	s_waitcnt lgkmcnt(2)
	v_mfma_f32_32x32x16_bf16 v[66:81], v[14:17], v[2:5], 0
	s_waitcnt lgkmcnt(1)
	v_mfma_f32_32x32x16_bf16 v[82:97], v[180:183], v[144:147], v[82:97]
	s_waitcnt lgkmcnt(0)
	v_mfma_f32_32x32x16_bf16 v[66:81], v[184:187], v[144:147], v[66:81]
	v_xor_b32_e32 v144, v188, v152
	v_lshl_add_u32 v144, v144, 4, v155
	ds_read_b128 v[144:147], v144
	v_mfma_f32_32x32x16_bf16 v[18:33], v[10:13], v[6:9], 0
	v_mfma_f32_32x32x16_bf16 v[2:17], v[14:17], v[6:9], 0
	v_mfma_f32_32x32x16_bf16 v[18:33], v[180:183], v[160:163], v[18:33]
	v_mfma_f32_32x32x16_bf16 v[2:17], v[184:187], v[160:163], v[2:17]
	ds_read_b128 v[160:163], v153
	s_waitcnt lgkmcnt(1)
	v_mfma_f32_32x32x16_bf16 v[114:129], v[144:147], v[148:151], v[114:129]
	s_waitcnt vmcnt(5)
	v_mfma_f32_32x32x16_bf16 v[50:65], v[144:147], v[164:167], v[50:65]
	v_xor_b32_e32 v144, v192, v152
	v_lshl_add_u32 v144, v144, 4, v191
	ds_read_b128 v[144:147], v144
	v_xor_b32_e32 v152, v194, v152
	v_lshl_add_u32 v152, v152, 4, v193
	s_waitcnt lgkmcnt(1)
	v_mfma_f32_32x32x16_bf16 v[98:113], v[160:163], v[148:151], v[98:113]
	v_mfma_f32_32x32x16_bf16 v[34:49], v[160:163], v[164:167], v[34:49]
	ds_read_b128 v[160:163], v152
	v_add_u32_e32 v152, 6, v140
	s_waitcnt lgkmcnt(1)
	v_mfma_f32_32x32x16_bf16 v[82:97], v[144:147], v[148:151], v[82:97]
	v_mfma_f32_32x32x16_bf16 v[18:33], v[144:147], v[164:167], v[18:33]
	v_xor_b32_e32 v144, v188, v152
	v_lshl_add_u32 v144, v144, 4, v155
	ds_read_b128 v[144:147], v144
	s_waitcnt lgkmcnt(1)
	v_mfma_f32_32x32x16_bf16 v[66:81], v[160:163], v[148:151], v[66:81]
	v_xor_b32_e32 v148, v190, v152
	v_lshl_add_u32 v148, v148, 4, v189
	ds_read_b128 v[148:151], v148
	s_waitcnt lgkmcnt(1)
	v_mfma_f32_32x32x16_bf16 v[114:129], v[144:147], v[156:159], v[114:129]
	s_waitcnt vmcnt(4)
	v_mfma_f32_32x32x16_bf16 v[50:65], v[144:147], v[168:171], v[50:65]
	v_xor_b32_e32 v144, v192, v152
	v_lshl_add_u32 v144, v144, 4, v191
	ds_read_b128 v[144:147], v144
	s_waitcnt lgkmcnt(1)
	v_mfma_f32_32x32x16_bf16 v[98:113], v[148:151], v[156:159], v[98:113]
	v_mfma_f32_32x32x16_bf16 v[34:49], v[148:151], v[168:171], v[34:49]
	v_xor_b32_e32 v148, v194, v152
	v_lshl_add_u32 v148, v148, 4, v193
	v_add_u32_e32 v152, 8, v140
	ds_read_b128 v[148:151], v148
	s_waitcnt lgkmcnt(1)
	v_mfma_f32_32x32x16_bf16 v[82:97], v[144:147], v[156:159], v[82:97]
	v_mfma_f32_32x32x16_bf16 v[18:33], v[144:147], v[168:171], v[18:33]
	v_xor_b32_e32 v144, v188, v152
	v_lshl_add_u32 v144, v144, 4, v155
	ds_read_b128 v[144:147], v144
	v_mfma_f32_32x32x16_bf16 v[2:17], v[160:163], v[164:167], v[2:17]
	s_waitcnt lgkmcnt(1)
	v_mfma_f32_32x32x16_bf16 v[66:81], v[148:151], v[156:159], v[66:81]
	v_or_b32_e32 v157, s21, v154
	v_or_b32_e32 v156, s50, v157
	v_mfma_f32_32x32x16_bf16 v[2:17], v[148:151], v[168:171], v[2:17]
	v_xor_b32_e32 v148, v190, v152
	v_lshl_add_u32 v148, v148, 4, v189
	ds_read_b128 v[148:151], v148
	s_waitcnt vmcnt(3) lgkmcnt(1)
	v_mfma_f32_32x32x16_bf16 v[50:65], v[144:147], v[172:175], v[50:65]
	v_xor_b32_e32 v144, v192, v152
	v_lshl_add_u32 v144, v144, 4, v191
	ds_read_b128 v[144:147], v144
	s_waitcnt lgkmcnt(1)
	v_mfma_f32_32x32x16_bf16 v[34:49], v[148:151], v[172:175], v[34:49]
	v_xor_b32_e32 v148, v194, v152
	v_lshl_add_u32 v148, v148, 4, v193
	v_add_u32_e32 v152, 10, v140
	ds_read_b128 v[148:151], v148
	s_waitcnt lgkmcnt(1)
	v_mfma_f32_32x32x16_bf16 v[18:33], v[144:147], v[172:175], v[18:33]
	v_xor_b32_e32 v144, v188, v152
	v_lshl_add_u32 v144, v144, 4, v155
	ds_read_b128 v[144:147], v144
	s_waitcnt lgkmcnt(1)
	v_mfma_f32_32x32x16_bf16 v[2:17], v[148:151], v[172:175], v[2:17]
	v_xor_b32_e32 v148, v190, v152
	v_lshl_add_u32 v148, v148, 4, v189
	ds_read_b128 v[148:151], v148
	s_waitcnt vmcnt(2) lgkmcnt(1)
	v_mfma_f32_32x32x16_bf16 v[50:65], v[144:147], v[176:179], v[50:65]
	v_xor_b32_e32 v144, v192, v152
	v_lshl_add_u32 v144, v144, 4, v191
	ds_read_b128 v[144:147], v144
	s_waitcnt lgkmcnt(1)
; #define LAS __attribute__((address_space(3)))
; __device__ __forceinline__ void gmlp_unit(const GmlpP& P, int b, int ch, LAS unsigned char* lds, int wave, int lane_in) {
;     ...
;         for (int ks = 0; ks < 8; ++ks)
; #pragma unroll
;             for (int mt = 0; mt < 4; ++mt) {
;                 const int cc = 32 * mt + r32;
;                 const bf16x8 a = *(const LAS bf16x8*)(lds + (gI * 128 + cc) * LDS_TT_PITCH + 16 * ((2 * ks + h) ^ ((cc >> 3) & 15)));
;                 if (ks < 4) acc[mt][0] = __builtin_amdgcn_mfma_f32_32x32x16_bf16(a, bw0[ks], acc[mt][0], 0, 0, 0);
;                 acc[mt][1] = __builtin_amdgcn_mfma_f32_32x32x16_bf16(a, bw1[ks], acc[mt][1], 0, 0, 0);
;                 if (mt == 3 && (ks & 1)) asm volatile("" ::: "memory");
;             }
;     }
;     LAS float* ssqg = (LAS float*)(lds + LDS_SSQG);
; #pragma unroll
;     for (int nt = 0; nt < 2; ++nt) {
;         const int t = 32 * (nt == 0 ? tt0 : tt1) + r32;
;         const float bsv = P.bs[gI * 128 + t];
;         const bf16_t* up = P.U + (tok0 + t) * GW + gI * 128 + 4 * h;
;         float ss = 0.f;
;         u32x2 uraw[4][4];
; #pragma unroll
;         for (int mt = 0; mt < 4; ++mt)
; #pragma unroll
;             for (int e4 = 0; e4 < 4; ++e4) uraw[mt][e4] = *(const u32x2*)(up + 32 * mt + 8 * e4);
; #pragma unroll
;         for (int mt = 0; mt < 4; ++mt)
; #pragma unroll
;             for (int e4 = 0; e4 < 4; ++e4) {
;                 const u32x2 raw = uraw[mt][e4];
;                 const float u0 = __builtin_bit_cast(float, raw.x << 16), u1 = __builtin_bit_cast(float, raw.x & 0xffff0000u);
;                 const float u2 = __builtin_bit_cast(float, raw.y << 16), u3 = __builtin_bit_cast(float, raw.y & 0xffff0000u);
;                 float m0 = u0 * (acc[mt][nt][4 * e4] + bsv), m1 = u1 * (acc[mt][nt][4 * e4 + 1] + bsv), m2 = u2 * (acc[mt][nt][4 * e4 + 2] + bsv), m3 = u3 * (acc[mt][nt][4 * e4 + 3] + bsv);
	v_mfma_f32_32x32x16_bf16 v[34:49], v[148:151], v[176:179], v[34:49]
	v_xor_b32_e32 v148, v194, v152
	v_lshl_add_u32 v148, v148, 4, v193
	v_add_u32_e32 v152, 12, v140
	ds_read_b128 v[148:151], v148
	s_waitcnt lgkmcnt(1)
	v_mfma_f32_32x32x16_bf16 v[18:33], v[144:147], v[176:179], v[18:33]
	v_xor_b32_e32 v144, v188, v152
	v_lshl_add_u32 v144, v144, 4, v155
	ds_read_b128 v[144:147], v144
	s_waitcnt lgkmcnt(1)
	v_mfma_f32_32x32x16_bf16 v[2:17], v[148:151], v[176:179], v[2:17]
	v_xor_b32_e32 v148, v190, v152
	v_lshl_add_u32 v148, v148, 4, v189
	ds_read_b128 v[148:151], v148
	s_waitcnt vmcnt(1) lgkmcnt(1)
	v_mfma_f32_32x32x16_bf16 v[50:65], v[144:147], v[134:137], v[50:65]
	v_xor_b32_e32 v144, v192, v152
	v_lshl_add_u32 v144, v144, 4, v191
	ds_read_b128 v[144:147], v144
	s_waitcnt lgkmcnt(1)
	v_mfma_f32_32x32x16_bf16 v[34:49], v[148:151], v[134:137], v[34:49]
	v_xor_b32_e32 v148, v194, v152
	v_lshl_add_u32 v148, v148, 4, v193
	ds_read_b128 v[150:153], v148
	v_or_b32_e32 v148, s6, v157
	v_ashrrev_i32_e32 v149, 31, v148
	v_lshl_add_u64 v[178:179], v[148:149], 2, s[40:41]
	s_waitcnt lgkmcnt(1)
	v_mfma_f32_32x32x16_bf16 v[18:33], v[144:147], v[134:137], v[18:33]
	v_add_u32_e32 v144, 14, v140
	v_xor_b32_e32 v145, v188, v144
	v_lshl_add_u32 v145, v145, 4, v155
	v_xor_b32_e32 v146, v190, v144
	v_lshl_add_u32 v146, v146, 4, v189
	ds_read_b128 v[158:161], v145
	ds_read_b128 v[162:165], v146
	v_xor_b32_e32 v145, v192, v144
	v_xor_b32_e32 v144, v194, v144
	v_lshl_add_u32 v145, v145, 4, v191
	v_lshl_add_u32 v144, v144, 4, v193
	ds_read_b128 v[166:169], v145
	ds_read_b128 v[170:173], v144
	v_lshlrev_b32_e32 v144, 2, v140
	v_ashrrev_i32_e32 v145, 31, v144
	v_lshl_add_u64 v[146:147], v[144:145], 1, s[14:15]
	v_lshlrev_b32_e32 v140, 10, v156
	v_lshl_add_u64 v[174:175], v[146:147], 0, v[140:141]
	global_load_dword v140, v[178:179], off
	v_bfe_u32 v234, v0, 5, 1
	v_lshlrev_b32_e32 v234, 3, v234
	v_mov_b32_e32 v235, 0
	v_lshl_add_u64 v[234:235], v[174:175], 0, v[234:235]
	global_load_dwordx4 v[202:205], v[234:235], off
	global_load_dwordx4 v[206:209], v[234:235], off offset:32
	global_load_dwordx4 v[210:213], v[234:235], off offset:64
	global_load_dwordx4 v[214:217], v[234:235], off offset:96
	global_load_dwordx4 v[218:221], v[234:235], off offset:128
	global_load_dwordx4 v[222:225], v[234:235], off offset:160
	global_load_dwordx4 v[226:229], v[234:235], off offset:192
	global_load_dwordx4 v[230:233], v[234:235], off offset:224
	s_waitcnt vmcnt(9) lgkmcnt(3)
	v_mfma_f32_32x32x16_bf16 v[50:65], v[158:161], v[130:133], v[50:65]
	s_waitcnt vmcnt(8)
	v_add_f32_e64 v114, v114, v140
	v_add_f32_e64 v115, v115, v140
	s_waitcnt lgkmcnt(2)
	v_mfma_f32_32x32x16_bf16 v[34:49], v[162:165], v[130:133], v[34:49]
	v_add_f32_e64 v116, v116, v140
	v_add_f32_e64 v117, v117, v140
	v_add_f32_e64 v118, v118, v140
	v_add_f32_e64 v119, v119, v140
	v_pk_add_f32 v[120:121], v[120:121], v[140:141] op_sel_hi:[1,0]
	v_pk_add_f32 v[122:123], v[122:123], v[140:141] op_sel_hi:[1,0]
	v_pk_add_f32 v[124:125], v[124:125], v[140:141] op_sel_hi:[1,0]
	v_pk_add_f32 v[126:127], v[126:127], v[140:141] op_sel_hi:[1,0]
	v_mfma_f32_32x32x16_bf16 v[2:17], v[150:153], v[134:137], v[2:17]
	v_add_f32_e64 v128, v128, v140
	v_add_f32_e64 v129, v129, v140
	v_add_f32_e64 v98, v98, v140
	v_add_f32_e64 v99, v99, v140
	v_add_f32_e64 v100, v100, v140
	v_add_f32_e64 v101, v101, v140
	v_pk_add_f32 v[102:103], v[102:103], v[140:141] op_sel_hi:[1,0]
	v_pk_add_f32 v[104:105], v[104:105], v[140:141] op_sel_hi:[1,0]
	v_pk_add_f32 v[106:107], v[106:107], v[140:141] op_sel_hi:[1,0]
	v_pk_add_f32 v[108:109], v[108:109], v[140:141] op_sel_hi:[1,0]
	s_waitcnt lgkmcnt(1)
	v_mfma_f32_32x32x16_bf16 v[18:33], v[166:169], v[130:133], v[18:33]
	v_add_f32_e64 v110, v110, v140
	v_add_f32_e64 v111, v111, v140
	v_add_f32_e64 v112, v112, v140
	v_add_f32_e64 v113, v113, v140
	v_add_f32_e64 v82, v82, v140
	v_add_f32_e64 v83, v83, v140
	v_pk_add_f32 v[84:85], v[84:85], v[140:141] op_sel_hi:[1,0]
	v_pk_add_f32 v[86:87], v[86:87], v[140:141] op_sel_hi:[1,0]
	v_pk_add_f32 v[88:89], v[88:89], v[140:141] op_sel_hi:[1,0]
	v_pk_add_f32 v[90:91], v[90:91], v[140:141] op_sel_hi:[1,0]
	s_waitcnt lgkmcnt(0)
	v_mfma_f32_32x32x16_bf16 v[2:17], v[170:173], v[130:133], v[2:17]
	s_waitcnt vmcnt(0)
; __device__ __forceinline__ void gmlp_unit(const GmlpP& P, int b, int ch, LAS unsigned char* lds, int wave, int lane_in) {
;     ...
;         for (int mt = 0; mt < 4; ++mt)
; #pragma unroll
;             for (int e4 = 0; e4 < 4; ++e4) uraw[mt][e4] = *(const u32x2*)(up + 32 * mt + 8 * e4);
; #pragma unroll
;         for (int mt = 0; mt < 4; ++mt)
; #pragma unroll
;             for (int e4 = 0; e4 < 4; ++e4) {
;                 const u32x2 raw = uraw[mt][e4];
;                 const float u0 = __builtin_bit_cast(float, raw.x << 16), u1 = __builtin_bit_cast(float, raw.x & 0xffff0000u);
;                 const float u2 = __builtin_bit_cast(float, raw.y << 16), u3 = __builtin_bit_cast(float, raw.y & 0xffff0000u);
;                 float m0 = u0 * (acc[mt][nt][4 * e4] + bsv), m1 = u1 * (acc[mt][nt][4 * e4 + 1] + bsv), m2 = u2 * (acc[mt][nt][4 * e4 + 2] + bsv), m3 = u3 * (acc[mt][nt][4 * e4 + 3] + bsv);
;                 acc[mt][nt][4 * e4] = m0; acc[mt][nt][4 * e4 + 1] = m1; acc[mt][nt][4 * e4 + 2] = m2; acc[mt][nt][4 * e4 + 3] = m3;
;                 ss += (m0 * m0 + m1 * m1) + (m2 * m2 + m3 * m3);
	v_permlane32_swap_b32_e32 v202, v204
	v_permlane32_swap_b32_e32 v203, v205
	v_permlane32_swap_b32_e32 v206, v208
	v_permlane32_swap_b32_e32 v207, v209
	v_permlane32_swap_b32_e32 v210, v212
	v_permlane32_swap_b32_e32 v211, v213
	v_permlane32_swap_b32_e32 v214, v216
	v_permlane32_swap_b32_e32 v215, v217
	v_permlane32_swap_b32_e32 v218, v220
	v_permlane32_swap_b32_e32 v219, v221
	v_permlane32_swap_b32_e32 v222, v224
	v_permlane32_swap_b32_e32 v223, v225
	v_permlane32_swap_b32_e32 v226, v228
	v_permlane32_swap_b32_e32 v227, v229
	v_permlane32_swap_b32_e32 v230, v232
	v_permlane32_swap_b32_e32 v231, v233
	v_mov_b32_e32 v176, v202
	v_mov_b32_e32 v177, v203
	v_mov_b32_e32 v178, v204
	v_mov_b32_e32 v179, v205
	v_mov_b32_e32 v158, v206
	v_mov_b32_e32 v159, v207
	v_mov_b32_e32 v160, v208
	v_mov_b32_e32 v161, v209
	v_mov_b32_e32 v162, v210
	v_mov_b32_e32 v163, v211
	v_mov_b32_e32 v164, v212
	v_mov_b32_e32 v165, v213
	v_mov_b32_e32 v166, v214
	v_mov_b32_e32 v167, v215
	v_mov_b32_e32 v168, v216
	v_mov_b32_e32 v169, v217
	v_mov_b32_e32 v170, v218
	v_mov_b32_e32 v171, v219
	v_mov_b32_e32 v172, v220
	v_mov_b32_e32 v173, v221
	v_mov_b32_e32 v180, v222
	v_mov_b32_e32 v181, v223
	v_mov_b32_e32 v152, v224
	v_mov_b32_e32 v153, v225
	v_mov_b32_e32 v150, v226
	v_mov_b32_e32 v151, v227
	v_mov_b32_e32 v136, v228
	v_mov_b32_e32 v137, v229
	v_mov_b32_e32 v134, v230
	v_mov_b32_e32 v135, v231
	v_mov_b32_e32 v132, v232
	v_mov_b32_e32 v133, v233
	v_or_b32_e32 v236, s23, v154
	v_or_b32_e32 v236, s50, v236
	v_lshlrev_b32_e32 v236, 10, v236
	v_mov_b32_e32 v237, 0
	v_lshl_add_u64 v[236:237], v[146:147], 0, v[236:237]
	v_bfe_u32 v238, v0, 5, 1
	v_lshlrev_b32_e32 v238, 3, v238
	v_mov_b32_e32 v239, 0
	v_lshl_add_u64 v[236:237], v[236:237], 0, v[238:239]
	global_load_dwordx4 v[202:205], v[236:237], off
	global_load_dwordx4 v[206:209], v[236:237], off offset:32
	global_load_dwordx4 v[210:213], v[236:237], off offset:64
	global_load_dwordx4 v[214:217], v[236:237], off offset:96
	global_load_dwordx4 v[218:221], v[236:237], off offset:128
	global_load_dwordx4 v[222:225], v[236:237], off offset:160
	global_load_dwordx4 v[226:229], v[236:237], off offset:192
	global_load_dwordx4 v[230:233], v[236:237], off offset:224
	v_lshlrev_b32_e32 v130, 16, v176
	v_and_b32_e32 v131, 0xffff0000, v176
	v_pk_mul_f32 v[114:115], v[114:115], v[130:131]
	v_lshlrev_b32_e32 v130, 16, v177
	v_and_b32_e32 v131, 0xffff0000, v177
	v_pk_mul_f32 v[116:117], v[116:117], v[130:131]
	v_mul_f32_e32 v130, v115, v115
	v_mul_f32_e32 v174, v117, v117
	v_pk_fma_f32 v[130:131], v[114:115], v[114:115], v[130:131] op_sel_hi:[1,1,0]
	v_pk_fma_f32 v[174:175], v[116:117], v[116:117], v[174:175] op_sel_hi:[1,1,0]
	v_pk_add_f32 v[92:93], v[92:93], v[140:141] op_sel_hi:[1,0]
	v_pk_add_f32 v[174:175], v[130:131], v[174:175]
	v_lshlrev_b32_e32 v130, 16, v178
	v_and_b32_e32 v131, 0xffff0000, v178
	v_pk_mul_f32 v[118:119], v[118:119], v[130:131]
	v_lshlrev_b32_e32 v130, 16, v179
	v_and_b32_e32 v131, 0xffff0000, v179
	v_pk_mul_f32 v[130:131], v[120:121], v[130:131]
	v_mul_f32_e32 v120, v119, v119
	v_mul_f32_e32 v176, v131, v131
	v_pk_fma_f32 v[120:121], v[118:119], v[118:119], v[120:121] op_sel_hi:[1,1,0]
	v_pk_fma_f32 v[176:177], v[130:131], v[130:131], v[176:177] op_sel_hi:[1,1,0]
	v_pk_add_f32 v[94:95], v[94:95], v[140:141] op_sel_hi:[1,0]
	v_pk_add_f32 v[120:121], v[120:121], v[176:177]
	v_pk_add_f32 v[96:97], v[96:97], v[140:141] op_sel_hi:[1,0]
	v_pk_add_f32 v[174:175], v[174:175], v[120:121]
	v_lshlrev_b32_e32 v120, 16, v158
	v_and_b32_e32 v121, 0xffff0000, v158
	v_pk_mul_f32 v[122:123], v[122:123], v[120:121]
	v_lshlrev_b32_e32 v120, 16, v159
	v_and_b32_e32 v121, 0xffff0000, v159
	v_pk_mul_f32 v[120:121], v[124:125], v[120:121]
	v_mul_f32_e32 v124, v123, v123
	v_mul_f32_e32 v158, v121, v121
	v_pk_fma_f32 v[124:125], v[122:123], v[122:123], v[124:125] op_sel_hi:[1,1,0]
	v_pk_fma_f32 v[158:159], v[120:121], v[120:121], v[158:159] op_sel_hi:[1,1,0]
	v_pk_add_f32 v[66:67], v[66:67], v[140:141] op_sel_hi:[1,0]
	v_pk_add_f32 v[124:125], v[124:125], v[158:159]
	v_pk_add_f32 v[68:69], v[68:69], v[140:141] op_sel_hi:[1,0]
	v_pk_add_f32 v[158:159], v[174:175], v[124:125]
	v_lshlrev_b32_e32 v124, 16, v160
	v_and_b32_e32 v125, 0xffff0000, v160
	v_pk_mul_f32 v[124:125], v[126:127], v[124:125]
	v_lshlrev_b32_e32 v126, 16, v161
	v_and_b32_e32 v127, 0xffff0000, v161
	v_pk_mul_f32 v[126:127], v[128:129], v[126:127]
	v_mul_f32_e32 v128, v125, v125
	v_mul_f32_e32 v160, v127, v127
	v_pk_fma_f32 v[128:129], v[124:125], v[124:125], v[128:129] op_sel_hi:[1,1,0]
	v_pk_fma_f32 v[160:161], v[126:127], v[126:127], v[160:161] op_sel_hi:[1,1,0]
	v_pk_add_f32 v[70:71], v[70:71], v[140:141] op_sel_hi:[1,0]
	v_pk_add_f32 v[128:129], v[128:129], v[160:161]
	v_pk_add_f32 v[72:73], v[72:73], v[140:141] op_sel_hi:[1,0]
	v_pk_add_f32 v[128:129], v[158:159], v[128:129]
	v_pk_add_f32 v[74:75], v[74:75], v[140:141] op_sel_hi:[1,0]
	v_lshlrev_b32_e32 v158, 16, v162
	v_and_b32_e32 v159, 0xffff0000, v162
	v_pk_mul_f32 v[98:99], v[98:99], v[158:159]
	v_lshlrev_b32_e32 v158, 16, v163
	v_and_b32_e32 v159, 0xffff0000, v163
	v_pk_mul_f32 v[100:101], v[100:101], v[158:159]
	v_mul_f32_e32 v158, v99, v99
	v_mul_f32_e32 v160, v101, v101
	v_pk_fma_f32 v[158:159], v[98:99], v[98:99], v[158:159] op_sel_hi:[1,1,0]
	v_pk_fma_f32 v[160:161], v[100:101], v[100:101], v[160:161] op_sel_hi:[1,1,0]
	v_pk_add_f32 v[76:77], v[76:77], v[140:141] op_sel_hi:[1,0]
	v_pk_add_f32 v[158:159], v[158:159], v[160:161]
	v_pk_add_f32 v[78:79], v[78:79], v[140:141] op_sel_hi:[1,0]
	v_pk_add_f32 v[158:159], v[128:129], v[158:159]
	v_lshlrev_b32_e32 v128, 16, v164
	v_and_b32_e32 v129, 0xffff0000, v164
; __device__ __forceinline__ void gmlp_unit(const GmlpP& P, int b, int ch, LAS unsigned char* lds, int wave, int lane_in) {
;     ...
;         const int t = 32 * (nt == 0 ? tt0 : tt1) + r32;
;         const float bsv = P.bs[gI * 128 + t];
;         const bf16_t* up = P.U + (tok0 + t) * GW + gI * 128 + 4 * h;
;         float ss = 0.f;
;         u32x2 uraw[4][4];
; #pragma unroll
;         for (int mt = 0; mt < 4; ++mt)
; #pragma unroll
;             for (int e4 = 0; e4 < 4; ++e4) uraw[mt][e4] = *(const u32x2*)(up + 32 * mt + 8 * e4);
; #pragma unroll
;         for (int mt = 0; mt < 4; ++mt)
; #pragma unroll
;             for (int e4 = 0; e4 < 4; ++e4) {
;                 const u32x2 raw = uraw[mt][e4];
;                 const float u0 = __builtin_bit_cast(float, raw.x << 16), u1 = __builtin_bit_cast(float, raw.x & 0xffff0000u);
;                 const float u2 = __builtin_bit_cast(float, raw.y << 16), u3 = __builtin_bit_cast(float, raw.y & 0xffff0000u);
;                 float m0 = u0 * (acc[mt][nt][4 * e4] + bsv), m1 = u1 * (acc[mt][nt][4 * e4 + 1] + bsv), m2 = u2 * (acc[mt][nt][4 * e4 + 2] + bsv), m3 = u3 * (acc[mt][nt][4 * e4 + 3] + bsv);
;                 acc[mt][nt][4 * e4] = m0; acc[mt][nt][4 * e4 + 1] = m1; acc[mt][nt][4 * e4 + 2] = m2; acc[mt][nt][4 * e4 + 3] = m3;
;                 ss += (m0 * m0 + m1 * m1) + (m2 * m2 + m3 * m3);
;             }
;         ss = xor32_sum(ss);
;         if (h == 0) ssqg[gI * 128 + t] = ss;
	v_pk_mul_f32 v[102:103], v[102:103], v[128:129]
	v_lshlrev_b32_e32 v128, 16, v165
	v_and_b32_e32 v129, 0xffff0000, v165
	v_pk_mul_f32 v[128:129], v[104:105], v[128:129]
	v_mul_f32_e32 v104, v103, v103
	v_mul_f32_e32 v160, v129, v129
	v_pk_fma_f32 v[104:105], v[102:103], v[102:103], v[104:105] op_sel_hi:[1,1,0]
	v_pk_fma_f32 v[160:161], v[128:129], v[128:129], v[160:161] op_sel_hi:[1,1,0]
	v_pk_add_f32 v[80:81], v[80:81], v[140:141] op_sel_hi:[1,0]
	v_pk_add_f32 v[104:105], v[104:105], v[160:161]
	s_nop 0
	v_pk_add_f32 v[158:159], v[158:159], v[104:105]
	v_lshlrev_b32_e32 v104, 16, v166
	v_and_b32_e32 v105, 0xffff0000, v166
	v_pk_mul_f32 v[106:107], v[106:107], v[104:105]
	v_lshlrev_b32_e32 v104, 16, v167
	v_and_b32_e32 v105, 0xffff0000, v167
	v_pk_mul_f32 v[104:105], v[108:109], v[104:105]
	v_mul_f32_e32 v108, v107, v107
	v_mul_f32_e32 v160, v105, v105
	v_pk_fma_f32 v[108:109], v[106:107], v[106:107], v[108:109] op_sel_hi:[1,1,0]
	v_pk_fma_f32 v[160:161], v[104:105], v[104:105], v[160:161] op_sel_hi:[1,1,0]
	s_nop 0
	v_pk_add_f32 v[108:109], v[108:109], v[160:161]
	s_nop 0
	v_pk_add_f32 v[158:159], v[158:159], v[108:109]
	v_lshlrev_b32_e32 v108, 16, v168
	v_and_b32_e32 v109, 0xffff0000, v168
	v_pk_mul_f32 v[108:109], v[110:111], v[108:109]
	v_lshlrev_b32_e32 v110, 16, v169
	v_and_b32_e32 v111, 0xffff0000, v169
	v_pk_mul_f32 v[110:111], v[112:113], v[110:111]
	v_mul_f32_e32 v112, v109, v109
	v_mul_f32_e32 v160, v111, v111
	v_pk_fma_f32 v[112:113], v[108:109], v[108:109], v[112:113] op_sel_hi:[1,1,0]
	v_pk_fma_f32 v[160:161], v[110:111], v[110:111], v[160:161] op_sel_hi:[1,1,0]
	s_nop 0
	v_pk_add_f32 v[112:113], v[112:113], v[160:161]
	s_nop 0
	v_pk_add_f32 v[112:113], v[158:159], v[112:113]
	v_lshlrev_b32_e32 v158, 16, v170
	v_and_b32_e32 v159, 0xffff0000, v170
	v_pk_mul_f32 v[82:83], v[82:83], v[158:159]
	v_lshlrev_b32_e32 v158, 16, v171
	v_and_b32_e32 v159, 0xffff0000, v171
	v_pk_mul_f32 v[84:85], v[84:85], v[158:159]
	v_mul_f32_e32 v158, v83, v83
	v_mul_f32_e32 v160, v85, v85
	v_pk_fma_f32 v[158:159], v[82:83], v[82:83], v[158:159] op_sel_hi:[1,1,0]
	v_pk_fma_f32 v[160:161], v[84:85], v[84:85], v[160:161] op_sel_hi:[1,1,0]
	s_nop 0
	v_pk_add_f32 v[158:159], v[158:159], v[160:161]
	s_nop 0
	v_pk_add_f32 v[158:159], v[112:113], v[158:159]
	v_lshlrev_b32_e32 v112, 16, v172
	v_and_b32_e32 v113, 0xffff0000, v172
	v_pk_mul_f32 v[86:87], v[86:87], v[112:113]
	v_lshlrev_b32_e32 v112, 16, v173
	v_and_b32_e32 v113, 0xffff0000, v173
	v_pk_mul_f32 v[112:113], v[88:89], v[112:113]
	v_mul_f32_e32 v88, v87, v87
	v_mul_f32_e32 v160, v113, v113
	v_pk_fma_f32 v[88:89], v[86:87], v[86:87], v[88:89] op_sel_hi:[1,1,0]
	v_pk_fma_f32 v[160:161], v[112:113], v[112:113], v[160:161] op_sel_hi:[1,1,0]
	s_nop 0
	v_pk_add_f32 v[88:89], v[88:89], v[160:161]
	s_nop 0
	v_pk_add_f32 v[158:159], v[158:159], v[88:89]
	v_lshlrev_b32_e32 v88, 16, v180
	v_and_b32_e32 v89, 0xffff0000, v180
	v_pk_mul_f32 v[90:91], v[90:91], v[88:89]
	v_lshlrev_b32_e32 v88, 16, v181
	v_and_b32_e32 v89, 0xffff0000, v181
	v_pk_mul_f32 v[88:89], v[92:93], v[88:89]
	v_mul_f32_e32 v92, v91, v91
	v_mul_f32_e32 v160, v89, v89
	v_pk_fma_f32 v[92:93], v[90:91], v[90:91], v[92:93] op_sel_hi:[1,1,0]
	v_pk_fma_f32 v[160:161], v[88:89], v[88:89], v[160:161] op_sel_hi:[1,1,0]
	s_nop 0
	v_pk_add_f32 v[92:93], v[92:93], v[160:161]
	s_nop 0
	v_pk_add_f32 v[158:159], v[158:159], v[92:93]
	v_lshlrev_b32_e32 v92, 16, v152
	v_and_b32_e32 v93, 0xffff0000, v152
	v_pk_mul_f32 v[92:93], v[94:95], v[92:93]
	v_lshlrev_b32_e32 v94, 16, v153
	v_and_b32_e32 v95, 0xffff0000, v153
	v_pk_mul_f32 v[94:95], v[96:97], v[94:95]
	v_mul_f32_e32 v96, v93, v93
	v_mul_f32_e32 v152, v95, v95
	v_pk_fma_f32 v[96:97], v[92:93], v[92:93], v[96:97] op_sel_hi:[1,1,0]
	v_pk_fma_f32 v[152:153], v[94:95], v[94:95], v[152:153] op_sel_hi:[1,1,0]
	s_nop 0
	v_pk_add_f32 v[96:97], v[96:97], v[152:153]
	v_lshlrev_b32_e32 v152, 16, v150
	v_and_b32_e32 v153, 0xffff0000, v150
	v_lshlrev_b32_e32 v150, 16, v151
	v_and_b32_e32 v151, 0xffff0000, v151
	v_pk_mul_f32 v[66:67], v[66:67], v[152:153]
	v_pk_mul_f32 v[68:69], v[68:69], v[150:151]
	v_mul_f32_e32 v150, v67, v67
	v_mul_f32_e32 v152, v69, v69
	v_pk_fma_f32 v[150:151], v[66:67], v[66:67], v[150:151] op_sel_hi:[1,1,0]
	v_pk_fma_f32 v[152:153], v[68:69], v[68:69], v[152:153] op_sel_hi:[1,1,0]
	v_pk_add_f32 v[96:97], v[158:159], v[96:97]
	v_pk_add_f32 v[150:151], v[150:151], v[152:153]
	s_nop 0
	v_pk_add_f32 v[150:151], v[96:97], v[150:151]
	v_lshlrev_b32_e32 v96, 16, v136
	v_and_b32_e32 v97, 0xffff0000, v136
	v_pk_mul_f32 v[70:71], v[70:71], v[96:97]
	v_lshlrev_b32_e32 v96, 16, v137
	v_and_b32_e32 v97, 0xffff0000, v137
	v_pk_mul_f32 v[96:97], v[72:73], v[96:97]
	v_mul_f32_e32 v72, v71, v71
	v_mul_f32_e32 v136, v97, v97
	v_pk_fma_f32 v[72:73], v[70:71], v[70:71], v[72:73] op_sel_hi:[1,1,0]
	v_pk_fma_f32 v[136:137], v[96:97], v[96:97], v[136:137] op_sel_hi:[1,1,0]
	s_nop 0
	v_pk_add_f32 v[72:73], v[72:73], v[136:137]
	s_nop 0
	v_pk_add_f32 v[136:137], v[150:151], v[72:73]
	v_lshlrev_b32_e32 v72, 16, v134
	v_and_b32_e32 v73, 0xffff0000, v134
	v_pk_mul_f32 v[74:75], v[74:75], v[72:73]
	v_lshlrev_b32_e32 v72, 16, v135
	v_and_b32_e32 v73, 0xffff0000, v135
	v_pk_mul_f32 v[72:73], v[76:77], v[72:73]
	v_mul_f32_e32 v76, v75, v75
	v_mul_f32_e32 v134, v73, v73
	v_pk_fma_f32 v[76:77], v[74:75], v[74:75], v[76:77] op_sel_hi:[1,1,0]
	v_pk_fma_f32 v[134:135], v[72:73], v[72:73], v[134:135] op_sel_hi:[1,1,0]
	s_nop 0
	v_pk_add_f32 v[76:77], v[76:77], v[134:135]
	s_nop 0
	v_pk_add_f32 v[134:135], v[136:137], v[76:77]
	v_lshlrev_b32_e32 v76, 16, v132
	v_and_b32_e32 v77, 0xffff0000, v132
	v_pk_mul_f32 v[76:77], v[78:79], v[76:77]
	v_lshlrev_b32_e32 v78, 16, v133
	v_and_b32_e32 v79, 0xffff0000, v133
	v_pk_mul_f32 v[78:79], v[80:81], v[78:79]
	v_mul_f32_e32 v80, v77, v77
	v_mul_f32_e32 v132, v79, v79
	v_pk_fma_f32 v[80:81], v[76:77], v[76:77], v[80:81] op_sel_hi:[1,1,0]
	v_pk_fma_f32 v[132:133], v[78:79], v[78:79], v[132:133] op_sel_hi:[1,1,0]
	s_nop 0
	v_pk_add_f32 v[80:81], v[80:81], v[132:133]
	s_nop 0
	v_pk_add_f32 v[80:81], v[134:135], v[80:81]
	s_nop 0
	v_mov_b32_e32 v81, v80
	s_nop 1
	v_permlane32_swap_b32_e32 v80, v81
	s_and_saveexec_b64 s[26:27], vcc
	v_add_f32_e32 v80, v80, v81
	v_lshl_add_u32 v81, v148, 2, 0
	v_add_u32_e32 v81, 0x22000, v81
	ds_write_b32 v81, v80
	s_or_b64 exec, exec, s[26:27]
	v_add_u32_e32 v140, s31, v154
	v_lshl_add_u64 v[80:81], v[140:141], 0, s[6:7]
	v_lshl_add_u64 v[80:81], v[80:81], 2, s[40:41]
	global_load_dword v150, v[80:81], off offset:256
	v_or_b32_e32 v158, s23, v154
	v_or_b32_e32 v139, s50, v158
	v_lshlrev_b32_e32 v140, 10, v139
	v_lshl_add_u64 v[152:153], v[146:147], 0, v[140:141]
	s_waitcnt vmcnt(0)
; __device__ __forceinline__ void gmlp_unit(const GmlpP& P, int b, int ch, LAS unsigned char* lds, int wave, int lane_in) {
;     ...
;         for (int mt = 0; mt < 4; ++mt)
; #pragma unroll
;             for (int e4 = 0; e4 < 4; ++e4) uraw[mt][e4] = *(const u32x2*)(up + 32 * mt + 8 * e4);
; #pragma unroll
;         for (int mt = 0; mt < 4; ++mt)
; #pragma unroll
;             for (int e4 = 0; e4 < 4; ++e4) {
;                 const u32x2 raw = uraw[mt][e4];
;                 const float u0 = __builtin_bit_cast(float, raw.x << 16), u1 = __builtin_bit_cast(float, raw.x & 0xffff0000u);
;                 const float u2 = __builtin_bit_cast(float, raw.y << 16), u3 = __builtin_bit_cast(float, raw.y & 0xffff0000u);
;                 float m0 = u0 * (acc[mt][nt][4 * e4] + bsv), m1 = u1 * (acc[mt][nt][4 * e4 + 1] + bsv), m2 = u2 * (acc[mt][nt][4 * e4 + 2] + bsv), m3 = u3 * (acc[mt][nt][4 * e4 + 3] + bsv);
;                 acc[mt][nt][4 * e4] = m0; acc[mt][nt][4 * e4 + 1] = m1; acc[mt][nt][4 * e4 + 2] = m2; acc[mt][nt][4 * e4 + 3] = m3;
;                 ss += (m0 * m0 + m1 * m1) + (m2 * m2 + m3 * m3);
	v_permlane32_swap_b32_e32 v202, v204
	v_permlane32_swap_b32_e32 v203, v205
	v_permlane32_swap_b32_e32 v206, v208
	v_permlane32_swap_b32_e32 v207, v209
	v_permlane32_swap_b32_e32 v210, v212
	v_permlane32_swap_b32_e32 v211, v213
	v_permlane32_swap_b32_e32 v214, v216
	v_permlane32_swap_b32_e32 v215, v217
	v_permlane32_swap_b32_e32 v218, v220
	v_permlane32_swap_b32_e32 v219, v221
	v_permlane32_swap_b32_e32 v222, v224
	v_permlane32_swap_b32_e32 v223, v225
	v_permlane32_swap_b32_e32 v226, v228
	v_permlane32_swap_b32_e32 v227, v229
	v_permlane32_swap_b32_e32 v230, v232
	v_permlane32_swap_b32_e32 v231, v233
	v_mov_b32_e32 v160, v202
	v_mov_b32_e32 v161, v203
	v_mov_b32_e32 v162, v204
	v_mov_b32_e32 v163, v205
	v_mov_b32_e32 v164, v206
	v_mov_b32_e32 v165, v207
	v_mov_b32_e32 v166, v208
	v_mov_b32_e32 v167, v209
	v_mov_b32_e32 v168, v210
	v_mov_b32_e32 v169, v211
	v_mov_b32_e32 v170, v212
	v_mov_b32_e32 v171, v213
	v_mov_b32_e32 v172, v214
	v_mov_b32_e32 v173, v215
	v_mov_b32_e32 v174, v216
	v_mov_b32_e32 v175, v217
	v_mov_b32_e32 v154, v218
	v_mov_b32_e32 v155, v219
	v_mov_b32_e32 v146, v220
	v_mov_b32_e32 v147, v221
	v_mov_b32_e32 v134, v222
	v_mov_b32_e32 v135, v223
	v_mov_b32_e32 v80, v224
	v_mov_b32_e32 v81, v225
	v_mov_b32_e32 v132, v226
	v_mov_b32_e32 v133, v227
	v_mov_b32_e32 v136, v228
	v_mov_b32_e32 v137, v229
	v_mov_b32_e32 v148, v230
	v_mov_b32_e32 v149, v231
	v_mov_b32_e32 v152, v232
	v_mov_b32_e32 v153, v233
	s_waitcnt vmcnt(12)
	v_lshlrev_b32_e32 v186, 16, v166
	s_waitcnt vmcnt(11)
	v_lshlrev_b32_e32 v188, 16, v168
	v_and_b32_e32 v189, 0xffff0000, v168
	v_lshlrev_b32_e32 v168, 16, v169
	v_and_b32_e32 v169, 0xffff0000, v169
	v_and_b32_e32 v187, 0xffff0000, v166
	v_lshlrev_b32_e32 v166, 16, v167
	v_pk_add_f32 v[50:51], v[50:51], v[150:151] op_sel_hi:[1,0]
	v_pk_add_f32 v[52:53], v[52:53], v[150:151] op_sel_hi:[1,0]
	v_pk_add_f32 v[54:55], v[54:55], v[150:151] op_sel_hi:[1,0]
	v_pk_add_f32 v[56:57], v[56:57], v[150:151] op_sel_hi:[1,0]
	v_pk_add_f32 v[176:177], v[58:59], v[150:151] op_sel_hi:[1,0]
	v_pk_add_f32 v[178:179], v[60:61], v[150:151] op_sel_hi:[1,0]
	v_pk_add_f32 v[184:185], v[36:37], v[150:151] op_sel_hi:[1,0]
	v_lshlrev_b32_e32 v36, 16, v160
	v_and_b32_e32 v37, 0xffff0000, v160
	v_lshlrev_b32_e32 v58, 16, v161
	v_and_b32_e32 v59, 0xffff0000, v161
	v_lshlrev_b32_e32 v60, 16, v162
	v_and_b32_e32 v61, 0xffff0000, v162
	v_lshlrev_b32_e32 v160, 16, v163
	v_and_b32_e32 v161, 0xffff0000, v163
	v_pk_add_f32 v[180:181], v[62:63], v[150:151] op_sel_hi:[1,0]
	v_pk_add_f32 v[182:183], v[64:65], v[150:151] op_sel_hi:[1,0]
	v_lshlrev_b32_e32 v162, 16, v164
	v_and_b32_e32 v163, 0xffff0000, v164
	v_lshlrev_b32_e32 v164, 16, v165
	v_and_b32_e32 v165, 0xffff0000, v165
	v_pk_mul_f32 v[64:65], v[50:51], v[36:37]
	v_pk_mul_f32 v[62:63], v[52:53], v[58:59]
	v_pk_mul_f32 v[60:61], v[54:55], v[60:61]
	v_pk_mul_f32 v[58:59], v[56:57], v[160:161]
	v_pk_add_f32 v[34:35], v[34:35], v[150:151] op_sel_hi:[1,0]
	v_pk_mul_f32 v[56:57], v[176:177], v[162:163]
	v_pk_mul_f32 v[54:55], v[178:179], v[164:165]
	v_mul_f32_e32 v140, v65, v65
	v_mul_f32_e32 v160, v63, v63
	v_mul_f32_e32 v162, v61, v61
	v_mul_f32_e32 v164, v59, v59
	v_pk_mul_f32 v[36:37], v[34:35], v[188:189]
	v_pk_mul_f32 v[34:35], v[184:185], v[168:169]
	v_pk_fma_f32 v[184:185], v[64:65], v[64:65], v[140:141] op_sel_hi:[1,1,0]
	v_pk_fma_f32 v[160:161], v[62:63], v[62:63], v[160:161] op_sel_hi:[1,1,0]
	v_pk_fma_f32 v[162:163], v[60:61], v[60:61], v[162:163] op_sel_hi:[1,1,0]
	v_pk_fma_f32 v[164:165], v[58:59], v[58:59], v[164:165] op_sel_hi:[1,1,0]
	v_and_b32_e32 v167, 0xffff0000, v167
	v_pk_add_f32 v[160:161], v[184:185], v[160:161]
	v_pk_add_f32 v[162:163], v[162:163], v[164:165]
	v_pk_mul_f32 v[52:53], v[180:181], v[186:187]
	v_pk_mul_f32 v[50:51], v[182:183], v[166:167]
	v_mul_f32_e32 v166, v57, v57
	v_mul_f32_e32 v168, v55, v55
	v_pk_add_f32 v[160:161], v[160:161], v[162:163]
	s_waitcnt vmcnt(10)
	v_lshlrev_b32_e32 v162, 16, v170
	v_and_b32_e32 v163, 0xffff0000, v170
	v_pk_add_f32 v[38:39], v[38:39], v[150:151] op_sel_hi:[1,0]
	v_mul_f32_e32 v176, v53, v53
	v_mul_f32_e32 v178, v51, v51
	v_pk_fma_f32 v[166:167], v[56:57], v[56:57], v[166:167] op_sel_hi:[1,1,0]
	v_pk_fma_f32 v[168:169], v[54:55], v[54:55], v[168:169] op_sel_hi:[1,1,0]
	v_pk_mul_f32 v[38:39], v[38:39], v[162:163]
	v_lshlrev_b32_e32 v162, 16, v171
	v_and_b32_e32 v163, 0xffff0000, v171
	v_pk_add_f32 v[40:41], v[40:41], v[150:151] op_sel_hi:[1,0]
	v_mul_f32_e32 v180, v37, v37
	v_mul_f32_e32 v182, v35, v35
	v_pk_fma_f32 v[176:177], v[52:53], v[52:53], v[176:177] op_sel_hi:[1,1,0]
	v_pk_fma_f32 v[178:179], v[50:51], v[50:51], v[178:179] op_sel_hi:[1,1,0]
	v_pk_add_f32 v[164:165], v[166:167], v[168:169]
	v_pk_mul_f32 v[40:41], v[40:41], v[162:163]
	v_mul_f32_e32 v140, v39, v39
	v_pk_fma_f32 v[180:181], v[36:37], v[36:37], v[180:181] op_sel_hi:[1,1,0]
	v_pk_fma_f32 v[182:183], v[34:35], v[34:35], v[182:183] op_sel_hi:[1,1,0]
	v_pk_add_f32 v[166:167], v[176:177], v[178:179]
	v_pk_add_f32 v[160:161], v[160:161], v[164:165]
	v_pk_fma_f32 v[162:163], v[38:39], v[38:39], v[140:141] op_sel_hi:[1,1,0]
	v_mul_f32_e32 v140, v41, v41
	v_pk_add_f32 v[168:169], v[180:181], v[182:183]
	v_pk_add_f32 v[160:161], v[160:161], v[166:167]
	v_pk_fma_f32 v[164:165], v[40:41], v[40:41], v[140:141] op_sel_hi:[1,1,0]
	v_pk_add_f32 v[160:161], v[160:161], v[168:169]
	v_pk_add_f32 v[162:163], v[162:163], v[164:165]
	v_pk_add_f32 v[42:43], v[42:43], v[150:151] op_sel_hi:[1,0]
	v_pk_add_f32 v[160:161], v[160:161], v[162:163]
	s_waitcnt vmcnt(9)
; __device__ __forceinline__ void gmlp_unit(const GmlpP& P, int b, int ch, LAS unsigned char* lds, int wave, int lane_in) {
;     ...
;         for (int mt = 0; mt < 4; ++mt)
; #pragma unroll
;             for (int e4 = 0; e4 < 4; ++e4) uraw[mt][e4] = *(const u32x2*)(up + 32 * mt + 8 * e4);
; #pragma unroll
;         for (int mt = 0; mt < 4; ++mt)
; #pragma unroll
;             for (int e4 = 0; e4 < 4; ++e4) {
;                 const u32x2 raw = uraw[mt][e4];
;                 const float u0 = __builtin_bit_cast(float, raw.x << 16), u1 = __builtin_bit_cast(float, raw.x & 0xffff0000u);
;                 const float u2 = __builtin_bit_cast(float, raw.y << 16), u3 = __builtin_bit_cast(float, raw.y & 0xffff0000u);
;                 float m0 = u0 * (acc[mt][nt][4 * e4] + bsv), m1 = u1 * (acc[mt][nt][4 * e4 + 1] + bsv), m2 = u2 * (acc[mt][nt][4 * e4 + 2] + bsv), m3 = u3 * (acc[mt][nt][4 * e4 + 3] + bsv);
;                 acc[mt][nt][4 * e4] = m0; acc[mt][nt][4 * e4 + 1] = m1; acc[mt][nt][4 * e4 + 2] = m2; acc[mt][nt][4 * e4 + 3] = m3;
;                 ss += (m0 * m0 + m1 * m1) + (m2 * m2 + m3 * m3);
;             }
;         ss = xor32_sum(ss);
;         if (h == 0) ssqg[gI * 128 + t] = ss;
	v_lshlrev_b32_e32 v162, 16, v172
	v_and_b32_e32 v163, 0xffff0000, v172
	v_pk_mul_f32 v[42:43], v[42:43], v[162:163]
	v_lshlrev_b32_e32 v162, 16, v173
	v_and_b32_e32 v163, 0xffff0000, v173
	v_pk_add_f32 v[44:45], v[44:45], v[150:151] op_sel_hi:[1,0]
	v_mul_f32_e32 v140, v43, v43
	v_pk_mul_f32 v[44:45], v[44:45], v[162:163]
	v_pk_fma_f32 v[162:163], v[42:43], v[42:43], v[140:141] op_sel_hi:[1,1,0]
	v_mul_f32_e32 v140, v45, v45
	v_pk_fma_f32 v[164:165], v[44:45], v[44:45], v[140:141] op_sel_hi:[1,1,0]
	v_pk_add_f32 v[46:47], v[46:47], v[150:151] op_sel_hi:[1,0]
	v_pk_add_f32 v[162:163], v[162:163], v[164:165]
	v_pk_add_f32 v[48:49], v[48:49], v[150:151] op_sel_hi:[1,0]
	v_pk_add_f32 v[160:161], v[160:161], v[162:163]
	s_waitcnt vmcnt(8)
	v_lshlrev_b32_e32 v162, 16, v174
	v_and_b32_e32 v163, 0xffff0000, v174
	v_pk_mul_f32 v[46:47], v[46:47], v[162:163]
	v_lshlrev_b32_e32 v162, 16, v175
	v_and_b32_e32 v163, 0xffff0000, v175
	v_pk_mul_f32 v[48:49], v[48:49], v[162:163]
	v_mul_f32_e32 v140, v47, v47
	v_pk_fma_f32 v[162:163], v[46:47], v[46:47], v[140:141] op_sel_hi:[1,1,0]
	v_mul_f32_e32 v140, v49, v49
	v_pk_fma_f32 v[164:165], v[48:49], v[48:49], v[140:141] op_sel_hi:[1,1,0]
	v_pk_add_f32 v[18:19], v[18:19], v[150:151] op_sel_hi:[1,0]
	v_pk_add_f32 v[162:163], v[162:163], v[164:165]
	v_pk_add_f32 v[20:21], v[20:21], v[150:151] op_sel_hi:[1,0]
	v_pk_add_f32 v[160:161], v[160:161], v[162:163]
	s_waitcnt vmcnt(7)
	v_lshlrev_b32_e32 v162, 16, v154
	v_and_b32_e32 v163, 0xffff0000, v154
	v_pk_mul_f32 v[18:19], v[18:19], v[162:163]
	v_lshlrev_b32_e32 v154, 16, v155
	v_and_b32_e32 v155, 0xffff0000, v155
	v_pk_mul_f32 v[20:21], v[20:21], v[154:155]
	v_mul_f32_e32 v140, v19, v19
	v_pk_fma_f32 v[154:155], v[18:19], v[18:19], v[140:141] op_sel_hi:[1,1,0]
	v_mul_f32_e32 v140, v21, v21
	v_pk_fma_f32 v[162:163], v[20:21], v[20:21], v[140:141] op_sel_hi:[1,1,0]
	v_pk_add_f32 v[22:23], v[22:23], v[150:151] op_sel_hi:[1,0]
	v_pk_add_f32 v[154:155], v[154:155], v[162:163]
	v_pk_add_f32 v[24:25], v[24:25], v[150:151] op_sel_hi:[1,0]
	v_pk_add_f32 v[154:155], v[160:161], v[154:155]
	s_waitcnt vmcnt(6)
	v_lshlrev_b32_e32 v160, 16, v146
	v_and_b32_e32 v161, 0xffff0000, v146
	v_pk_mul_f32 v[22:23], v[22:23], v[160:161]
	v_lshlrev_b32_e32 v146, 16, v147
	v_and_b32_e32 v147, 0xffff0000, v147
	v_pk_mul_f32 v[24:25], v[24:25], v[146:147]
	v_mul_f32_e32 v140, v23, v23
	v_pk_fma_f32 v[146:147], v[22:23], v[22:23], v[140:141] op_sel_hi:[1,1,0]
	v_mul_f32_e32 v140, v25, v25
	v_pk_fma_f32 v[160:161], v[24:25], v[24:25], v[140:141] op_sel_hi:[1,1,0]
	v_pk_add_f32 v[26:27], v[26:27], v[150:151] op_sel_hi:[1,0]
	v_pk_add_f32 v[146:147], v[146:147], v[160:161]
	v_pk_add_f32 v[28:29], v[28:29], v[150:151] op_sel_hi:[1,0]
	v_pk_add_f32 v[146:147], v[154:155], v[146:147]
	s_waitcnt vmcnt(5)
	v_lshlrev_b32_e32 v154, 16, v134
	v_and_b32_e32 v155, 0xffff0000, v134
	v_lshlrev_b32_e32 v134, 16, v135
	v_and_b32_e32 v135, 0xffff0000, v135
	v_pk_mul_f32 v[26:27], v[26:27], v[154:155]
	v_pk_mul_f32 v[28:29], v[28:29], v[134:135]
	v_mul_f32_e32 v134, v27, v27
	v_mul_f32_e32 v140, v29, v29
	v_pk_fma_f32 v[134:135], v[26:27], v[26:27], v[134:135] op_sel_hi:[1,1,0]
	v_pk_fma_f32 v[154:155], v[28:29], v[28:29], v[140:141] op_sel_hi:[1,1,0]
	v_pk_add_f32 v[30:31], v[30:31], v[150:151] op_sel_hi:[1,0]
	v_pk_add_f32 v[134:135], v[134:135], v[154:155]
	v_pk_add_f32 v[32:33], v[32:33], v[150:151] op_sel_hi:[1,0]
	v_pk_add_f32 v[134:135], v[146:147], v[134:135]
	s_waitcnt vmcnt(4)
	v_lshlrev_b32_e32 v146, 16, v80
	v_and_b32_e32 v147, 0xffff0000, v80
	v_lshlrev_b32_e32 v80, 16, v81
	v_and_b32_e32 v81, 0xffff0000, v81
	v_pk_mul_f32 v[30:31], v[30:31], v[146:147]
	v_pk_mul_f32 v[32:33], v[32:33], v[80:81]
	v_mul_f32_e32 v80, v31, v31
	v_mul_f32_e32 v140, v33, v33
	v_pk_fma_f32 v[80:81], v[30:31], v[30:31], v[80:81] op_sel_hi:[1,1,0]
	v_pk_fma_f32 v[146:147], v[32:33], v[32:33], v[140:141] op_sel_hi:[1,1,0]
	v_pk_add_f32 v[2:3], v[2:3], v[150:151] op_sel_hi:[1,0]
	v_pk_add_f32 v[80:81], v[80:81], v[146:147]
	v_pk_add_f32 v[4:5], v[4:5], v[150:151] op_sel_hi:[1,0]
	v_pk_add_f32 v[134:135], v[134:135], v[80:81]
	s_waitcnt vmcnt(3)
	v_lshlrev_b32_e32 v80, 16, v132
	v_and_b32_e32 v81, 0xffff0000, v132
	v_pk_mul_f32 v[80:81], v[2:3], v[80:81]
	v_lshlrev_b32_e32 v2, 16, v133
	v_and_b32_e32 v3, 0xffff0000, v133
	v_pk_mul_f32 v[132:133], v[4:5], v[2:3]
	v_mul_f32_e32 v2, v81, v81
	v_mul_f32_e32 v4, v133, v133
	v_pk_fma_f32 v[2:3], v[80:81], v[80:81], v[2:3] op_sel_hi:[1,1,0]
	v_pk_fma_f32 v[4:5], v[132:133], v[132:133], v[4:5] op_sel_hi:[1,1,0]
	v_pk_add_f32 v[6:7], v[6:7], v[150:151] op_sel_hi:[1,0]
	v_pk_add_f32 v[2:3], v[2:3], v[4:5]
	s_waitcnt vmcnt(2)
	v_lshlrev_b32_e32 v4, 16, v136
	v_and_b32_e32 v5, 0xffff0000, v136
	v_pk_add_f32 v[2:3], v[134:135], v[2:3]
	v_pk_mul_f32 v[134:135], v[6:7], v[4:5]
	v_lshlrev_b32_e32 v4, 16, v137
	v_and_b32_e32 v5, 0xffff0000, v137
	v_pk_add_f32 v[6:7], v[8:9], v[150:151] op_sel_hi:[1,0]
	s_nop 0
	v_pk_mul_f32 v[136:137], v[6:7], v[4:5]
	v_mul_f32_e32 v4, v135, v135
	v_mul_f32_e32 v6, v137, v137
	v_pk_fma_f32 v[4:5], v[134:135], v[134:135], v[4:5] op_sel_hi:[1,1,0]
	v_pk_fma_f32 v[6:7], v[136:137], v[136:137], v[6:7] op_sel_hi:[1,1,0]
	s_nop 0
	v_pk_add_f32 v[4:5], v[4:5], v[6:7]
	v_pk_add_f32 v[6:7], v[10:11], v[150:151] op_sel_hi:[1,0]
	v_pk_add_f32 v[2:3], v[2:3], v[4:5]
	s_waitcnt vmcnt(1)
	v_lshlrev_b32_e32 v4, 16, v148
	v_and_b32_e32 v5, 0xffff0000, v148
	v_pk_mul_f32 v[146:147], v[6:7], v[4:5]
	v_lshlrev_b32_e32 v4, 16, v149
	v_and_b32_e32 v5, 0xffff0000, v149
	v_pk_add_f32 v[6:7], v[12:13], v[150:151] op_sel_hi:[1,0]
	s_nop 0
	v_pk_mul_f32 v[148:149], v[6:7], v[4:5]
	v_mul_f32_e32 v4, v147, v147
	v_mul_f32_e32 v6, v149, v149
	v_pk_fma_f32 v[4:5], v[146:147], v[146:147], v[4:5] op_sel_hi:[1,1,0]
	v_pk_fma_f32 v[6:7], v[148:149], v[148:149], v[6:7] op_sel_hi:[1,1,0]
	s_nop 0
	v_pk_add_f32 v[4:5], v[4:5], v[6:7]
	v_pk_add_f32 v[6:7], v[14:15], v[150:151] op_sel_hi:[1,0]
	v_pk_add_f32 v[2:3], v[2:3], v[4:5]
	s_waitcnt vmcnt(0)
	v_lshlrev_b32_e32 v4, 16, v152
	v_and_b32_e32 v5, 0xffff0000, v152
	v_pk_mul_f32 v[14:15], v[6:7], v[4:5]
	v_lshlrev_b32_e32 v4, 16, v153
	v_and_b32_e32 v5, 0xffff0000, v153
	v_pk_add_f32 v[6:7], v[16:17], v[150:151] op_sel_hi:[1,0]
	s_nop 0
	v_pk_mul_f32 v[16:17], v[6:7], v[4:5]
	v_mul_f32_e32 v4, v15, v15
	v_mul_f32_e32 v6, v17, v17
	v_pk_fma_f32 v[4:5], v[14:15], v[14:15], v[4:5] op_sel_hi:[1,1,0]
	v_pk_fma_f32 v[6:7], v[16:17], v[16:17], v[6:7] op_sel_hi:[1,1,0]
	s_nop 0
	v_pk_add_f32 v[4:5], v[4:5], v[6:7]
	s_nop 0
	v_pk_add_f32 v[2:3], v[2:3], v[4:5]
	s_nop 0
	v_mov_b32_e32 v3, v2
	s_nop 1
	v_permlane32_swap_b32_e32 v2, v3
	s_and_saveexec_b64 s[26:27], vcc
	s_cbranch_execz .LBB0_536
	v_or_b32_e32 v4, s6, v158
	v_add_f32_e32 v2, v2, v3
	v_lshl_add_u32 v3, v4, 2, 0
	v_add_u32_e32 v3, 0x22000, v3
	ds_write_b32 v3, v2
	s_branch .LBB0_536
